# slot-unrolled attention loop: LDS-DMA target slot is an immediate per copy (write-slot rotation removed)
# speedup vs baseline: 1.0089x; 1.0028x over previous
; #define MFMA16(a, b, c) __builtin_amdgcn_mfma_f32_16x16x32_f16((a), (b), (c), 0, 0, 0)
; template <bool SEL, bool GEN>
; DI void attn_step(const KF& kv, const int kb, const int t, const int lane, const bool selbit,
;                   const LAS float* tabh, const half8 (&q)[2][2], f32x4 (&O)[2][4], const float (&nR)[2], float (&l)[2]) {
;     ...
;       s[hp][kt] = MFMA16(kv.k[kt][0], q[hp][0], c0);
;       s[hp][kt] = MFMA16(kv.k[kt][1], q[hp][1], s[hp][kt]);
;     }
;   }
;   if (GEN) {
;     const int d0 = t - kb - fq * 4;
; #pragma unroll
;     for (int kt = 0; kt < 2; ++kt)
; #pragma unroll
;       for (int j = 0; j < 4; ++j) {
;         const int dist = d0 - (kt * 16 + j);
;         const bool bad = SEL ? (dist < 0) : ((unsigned)dist >= 512u);
;         const int ix = bad ? 130 : (dist > 128 ? 128 : dist);
; #pragma unroll
;         for (int hp = 0; hp < 2; ++hp) s[hp][kt][j] += tabh[hp * 132 + ix];
;       }
;   }
;   half8 pf[2];
; #pragma unroll
;   for (int hp = 0; hp < 2; ++hp) {
;     f32x4 p0, p1;
; #pragma unroll
;     for (int j = 0; j < 4; ++j) { p0[j] = __builtin_amdgcn_exp2f(s[hp][0][j]); p1[j] = __builtin_amdgcn_exp2f(s[hp][1][j]); }
;     l[hp] += ((p0[0] + p0[1]) + (p0[2] + p0[3])) + ((p1[0] + p1[1]) + (p1[2] + p1[3]));
;     pf[hp] = pack8(p0, p1);
;   }
; #pragma unroll
;   for (int dt = 0; dt < 4; ++dt)
; #pragma unroll
;     for (int hp = 0; hp < 2; ++hp) O[hp][dt] = MFMA16(kv.v[dt], pf[hp], O[hp][dt]);
.Lat_noga_xa0:
	v_exp_f32_e32 v198, v100
	v_exp_f32_e32 v199, v101
	v_exp_f32_e32 v200, v102
	v_exp_f32_e32 v201, v103
	v_exp_f32_e32 v202, v104
	v_exp_f32_e32 v203, v105
	v_exp_f32_e32 v204, v106
	v_exp_f32_e32 v205, v107
	v_exp_f32_e32 v206, v108
	v_exp_f32_e32 v207, v109
	v_exp_f32_e32 v208, v110
	v_exp_f32_e32 v209, v111
	v_exp_f32_e32 v210, v112
	v_exp_f32_e32 v211, v113
	v_exp_f32_e32 v212, v114
	v_exp_f32_e32 v213, v115
	v_cvt_pkrtz_f16_f32 v120, v198, v199
	v_cvt_pkrtz_f16_f32 v121, v200, v201
	v_cvt_pkrtz_f16_f32 v122, v202, v203
	v_cvt_pkrtz_f16_f32 v123, v204, v205
	v_cvt_pkrtz_f16_f32 v124, v206, v207
	v_cvt_pkrtz_f16_f32 v125, v208, v209
	v_cvt_pkrtz_f16_f32 v126, v210, v211
	v_cvt_pkrtz_f16_f32 v127, v212, v213
	s_waitcnt lgkmcnt(0)
	s_and_b32 s44, s12, 2
	s_or_b32 s44, s44, 1
	v_mfma_f32_16x16x32_f16 v[100:103], v[96:99], v[8:11], v[128:131]
	s_add_i32 s8, s45, 64
	s_min_i32 s8, s8, s14
	s_mul_i32 s8, s8, s42
	v_mfma_f32_16x16x32_f16 v[104:107], v[88:91], v[8:11], v[128:131]
	s_mov_b32 s9, 0
	v_lshl_add_u64 v[238:239], v[240:241], 0, s[8:9]
	s_add_i32 m0, s22, 0x1d880
	s_nop 0
	v_mfma_f32_16x16x32_f16 v[108:111], v[96:99], v[16:19], v[132:135]
	global_load_lds_dwordx4 v[238:239], off
	s_add_i32 s45, s45, 32
	s_add_i32 s41, s41, -1
	s_add_i32 s10, s45, 0x9f
	v_mfma_f32_16x16x32_f16 v[112:115], v[88:91], v[16:19], v[132:135]
	s_cmp_gt_i32 s10, s51
	s_cselect_b32 s11, 2, 0
	s_add_i32 s10, s45, 0x1f1
	s_cmp_le_i32 s10, s51
	v_mfma_f32_16x16x32_f16 v[100:103], v[92:95], v[12:15], v[100:103]
	s_cselect_b32 s10, 2, 0
	s_and_b32 s10, s10, s4
	s_or_b32 s11, s11, s10
	v_mfma_f32_16x16x32_f16 v[104:107], v[84:87], v[12:15], v[104:107]
	s_lshr_b32 s10, s45, 6
	v_bfe_u32 v66, v244, s10, 1
	v_cmp_ne_u32_e32 vcc, 0, v66
	s_cmp_lg_u64 vcc, 0
	v_mfma_f32_16x16x32_f16 v[108:111], v[92:95], v[20:23], v[108:111]
	s_cselect_b32 s10, 1, 0
	s_lshr_b32 s9, s11, 1
	s_or_b32 s10, s10, s9
	s_cmp_le_i32 s45, s15
	v_mfma_f32_16x16x32_f16 v[112:115], v[84:87], v[20:23], v[112:115]
	s_cselect_b32 s10, s10, 0
	s_cmp_ge_i32 s45, s40
	s_cselect_b32 s10, s10, 0
	s_or_b32 s12, s11, s10
	v_mfma_f32_16x16x32_f16 v[60:63], v[80:83], v[120:123], v[60:63]
	v_add_f32_e32 v214, v214, v198
	v_add_f32_e32 v215, v215, v199
	v_mfma_f32_16x16x32_f16 v[56:59], v[76:79], v[120:123], v[56:59]
	v_add_f32_e32 v216, v216, v200
	v_add_f32_e32 v217, v217, v201
	v_mfma_f32_16x16x32_f16 v[52:55], v[72:75], v[120:123], v[52:55]
	v_add_f32_e32 v214, v214, v202
	v_add_f32_e32 v215, v215, v203
	v_mfma_f32_16x16x32_f16 v[48:51], v[68:71], v[120:123], v[48:51]
	v_add_f32_e32 v216, v216, v204
	v_add_f32_e32 v217, v217, v205
	v_mfma_f32_16x16x32_f16 v[44:47], v[80:83], v[124:127], v[44:47]
	v_add_f32_e32 v218, v218, v206
	v_add_f32_e32 v219, v219, v207
	v_mfma_f32_16x16x32_f16 v[40:43], v[76:79], v[124:127], v[40:43]
	v_add_f32_e32 v220, v220, v208
	v_add_f32_e32 v221, v221, v209
	v_mfma_f32_16x16x32_f16 v[36:39], v[72:75], v[124:127], v[36:39]
	v_add_f32_e32 v218, v218, v210
	v_add_f32_e32 v219, v219, v211
	v_mfma_f32_16x16x32_f16 v[32:35], v[68:71], v[124:127], v[32:35]
	v_add_f32_e32 v220, v220, v212
	v_add_f32_e32 v221, v221, v213
	ds_read_b128 v[80:83], v65 offset:4096
	ds_read_b128 v[76:79], v65 offset:5120
	ds_read_b128 v[72:75], v65 offset:6144
	ds_read_b128 v[68:71], v65 offset:7168
	s_cmp_lg_u32 s41, 0
	s_cbranch_scc1 .Lat_xtop1
	s_branch .Lat_xexit
.Lat_xb0:
	s_waitcnt lgkmcnt(0)
	s_and_b32 s44, s12, 2
	s_or_b32 s44, s44, 1
	v_mfma_f32_16x16x32_f16 v[100:103], v[96:99], v[8:11], v[128:131]
	s_add_i32 s8, s45, 64
	s_min_i32 s8, s8, s14
	s_mul_i32 s8, s8, s42
	v_mfma_f32_16x16x32_f16 v[104:107], v[88:91], v[8:11], v[128:131]
	s_mov_b32 s9, 0
	v_lshl_add_u64 v[238:239], v[240:241], 0, s[8:9]
	s_add_i32 m0, s22, 0x1d880
	s_nop 0
	v_mfma_f32_16x16x32_f16 v[108:111], v[96:99], v[16:19], v[132:135]
	global_load_lds_dwordx4 v[238:239], off
	s_add_i32 s45, s45, 32
	s_add_i32 s41, s41, -1
	s_add_i32 s10, s45, 0x9f
	v_mfma_f32_16x16x32_f16 v[112:115], v[88:91], v[16:19], v[132:135]
	s_cmp_gt_i32 s10, s51
	s_cselect_b32 s11, 2, 0
	s_add_i32 s10, s45, 0x1f1
	s_cmp_le_i32 s10, s51
	v_mfma_f32_16x16x32_f16 v[100:103], v[92:95], v[12:15], v[100:103]
	s_cselect_b32 s10, 2, 0
	s_and_b32 s10, s10, s4
	s_or_b32 s11, s11, s10
	v_mfma_f32_16x16x32_f16 v[104:107], v[84:87], v[12:15], v[104:107]
	s_lshr_b32 s10, s45, 6
	v_bfe_u32 v66, v244, s10, 1
	v_cmp_ne_u32_e32 vcc, 0, v66
	s_cmp_lg_u64 vcc, 0
	v_mfma_f32_16x16x32_f16 v[108:111], v[92:95], v[20:23], v[108:111]
	s_cselect_b32 s10, 1, 0
	s_lshr_b32 s9, s11, 1
	s_or_b32 s10, s10, s9
	s_cmp_le_i32 s45, s15
	v_mfma_f32_16x16x32_f16 v[112:115], v[84:87], v[20:23], v[112:115]
	s_cselect_b32 s10, s10, 0
	s_cmp_ge_i32 s45, s40
	s_cselect_b32 s10, s10, 0
	s_or_b32 s12, s11, s10
	ds_read_b128 v[80:83], v65 offset:4096
	ds_read_b128 v[76:79], v65 offset:5120
	ds_read_b128 v[72:75], v65 offset:6144
	ds_read_b128 v[68:71], v65 offset:7168
	s_cmp_lg_u32 s41, 0
	s_cbranch_scc1 .Lat_xtop1
	s_branch .Lat_xexit

; #define MFMA16(a, b, c) __builtin_amdgcn_mfma_f32_16x16x32_f16((a), (b), (c), 0, 0, 0)
; template <bool SEL, bool GEN>
; DI void attn_step(const KF& kv, const int kb, const int t, const int lane, const bool selbit,
;                   const LAS float* tabh, const half8 (&q)[2][2], f32x4 (&O)[2][4], const float (&nR)[2], float (&l)[2]) {
;     ...
; #pragma unroll
;   for (int dt = 0; dt < 4; ++dt)
; #pragma unroll
;     for (int hp = 0; hp < 2; ++hp) O[hp][dt] = MFMA16(kv.v[dt], pf[hp], O[hp][dt]);
; DI void attn_phase(const Params& p, const int layer, const int wid_s) {
;     ...
;           if (kb > kmax_w || kb < lo_w) continue;
;           if (br == 1 && kb + 31 + 128 <= t0 && __ballot((selmask >> (kb >> 6)) & 1u) == 0ull) continue;
.Lat_noga_xc0:
	v_exp_f32_e32 v198, v100
	v_exp_f32_e32 v199, v101
	v_exp_f32_e32 v200, v102
	v_exp_f32_e32 v201, v103
	v_exp_f32_e32 v202, v104
	v_exp_f32_e32 v203, v105
	v_exp_f32_e32 v204, v106
	v_exp_f32_e32 v205, v107
	v_exp_f32_e32 v206, v108
	v_exp_f32_e32 v207, v109
	v_exp_f32_e32 v208, v110
	v_exp_f32_e32 v209, v111
	v_exp_f32_e32 v210, v112
	v_exp_f32_e32 v211, v113
	v_exp_f32_e32 v212, v114
	v_exp_f32_e32 v213, v115
	v_cvt_pkrtz_f16_f32 v120, v198, v199
	v_cvt_pkrtz_f16_f32 v121, v200, v201
	v_cvt_pkrtz_f16_f32 v122, v202, v203
	v_cvt_pkrtz_f16_f32 v123, v204, v205
	v_cvt_pkrtz_f16_f32 v124, v206, v207
	v_cvt_pkrtz_f16_f32 v125, v208, v209
	v_cvt_pkrtz_f16_f32 v126, v210, v211
	v_cvt_pkrtz_f16_f32 v127, v212, v213
	s_waitcnt lgkmcnt(0)
	v_mfma_f32_16x16x32_f16 v[60:63], v[80:83], v[120:123], v[60:63]
	v_add_f32_e32 v214, v214, v198
	v_add_f32_e32 v215, v215, v199
	v_add_f32_e32 v216, v216, v200
	v_add_f32_e32 v217, v217, v201
	v_add_f32_e32 v214, v214, v202
	v_mfma_f32_16x16x32_f16 v[56:59], v[76:79], v[120:123], v[56:59]
	v_add_f32_e32 v215, v215, v203
	v_add_f32_e32 v216, v216, v204
	v_add_f32_e32 v217, v217, v205
	v_add_f32_e32 v218, v218, v206
	v_add_f32_e32 v219, v219, v207
	v_add_f32_e32 v220, v220, v208
	v_mfma_f32_16x16x32_f16 v[52:55], v[72:75], v[120:123], v[52:55]
	v_add_f32_e32 v221, v221, v209
	v_add_f32_e32 v218, v218, v210
	v_add_f32_e32 v219, v219, v211
	v_add_f32_e32 v220, v220, v212
	v_add_f32_e32 v221, v221, v213
	s_add_i32 s8, s45, 64
	v_mfma_f32_16x16x32_f16 v[48:51], v[68:71], v[120:123], v[48:51]
	s_min_i32 s8, s8, s14
	s_mul_i32 s8, s8, s42
	s_mov_b32 s9, 0
	v_lshl_add_u64 v[238:239], v[240:241], 0, s[8:9]
	s_add_i32 m0, s22, 0x1d880
	s_nop 0
	v_mfma_f32_16x16x32_f16 v[44:47], v[80:83], v[124:127], v[44:47]
	global_load_lds_dwordx4 v[238:239], off
	s_add_i32 s45, s45, 32
	s_add_i32 s41, s41, -1
	s_add_i32 s10, s45, 0x9f
	s_cmp_gt_i32 s10, s51
	v_mfma_f32_16x16x32_f16 v[40:43], v[76:79], v[124:127], v[40:43]
	s_cselect_b32 s11, 2, 0
	s_add_i32 s10, s45, 0x1f1
	s_cmp_le_i32 s10, s51
	s_cselect_b32 s10, 2, 0
	s_and_b32 s10, s10, s4
	s_or_b32 s11, s11, s10
	v_mfma_f32_16x16x32_f16 v[36:39], v[72:75], v[124:127], v[36:39]
	s_lshr_b32 s10, s45, 6
	v_bfe_u32 v66, v244, s10, 1
	v_cmp_ne_u32_e32 vcc, 0, v66
	s_cmp_lg_u64 vcc, 0
	s_cselect_b32 s10, 1, 0
	s_lshr_b32 s9, s11, 1
	v_mfma_f32_16x16x32_f16 v[32:35], v[68:71], v[124:127], v[32:35]
	s_or_b32 s10, s10, s9
	s_cmp_le_i32 s45, s15
	s_cselect_b32 s10, s10, 0
	s_cmp_ge_i32 s45, s40
	s_cselect_b32 s10, s10, 0
	s_or_b32 s12, s11, s10
	s_mov_b32 s44, 0
	s_cmp_lg_u32 s41, 0
	s_cbranch_scc1 .Lat_xtop1
	s_branch .Lat_xexit
.Lat_xd0:
	s_add_i32 s8, s45, 64
	s_min_i32 s8, s8, s14
	s_mul_i32 s8, s8, s42
	s_mov_b32 s9, 0
	v_lshl_add_u64 v[238:239], v[240:241], 0, s[8:9]
	s_add_i32 m0, s22, 0x1d880
	s_nop 0
	global_load_lds_dwordx4 v[238:239], off
	s_add_i32 s45, s45, 32
	s_add_i32 s41, s41, -1
	s_add_i32 s10, s45, 0x9f
	s_cmp_gt_i32 s10, s51
	s_cselect_b32 s11, 2, 0
	s_add_i32 s10, s45, 0x1f1
	s_cmp_le_i32 s10, s51
	s_cselect_b32 s10, 2, 0
	s_and_b32 s10, s10, s4
	s_or_b32 s11, s11, s10
	s_lshr_b32 s10, s45, 6
	v_bfe_u32 v66, v244, s10, 1
	v_cmp_ne_u32_e32 vcc, 0, v66
	s_cmp_lg_u64 vcc, 0
	s_cselect_b32 s10, 1, 0
	s_lshr_b32 s9, s11, 1
	s_or_b32 s10, s10, s9
	s_cmp_le_i32 s45, s15
	s_cselect_b32 s10, s10, 0
	s_cmp_ge_i32 s45, s40
	s_cselect_b32 s10, s10, 0
	s_or_b32 s12, s11, s10
	s_cmp_lg_u32 s41, 0
	s_cbranch_scc1 .Lat_xtop1
	s_branch .Lat_xexit

; #define MFMA16(a, b, c) __builtin_amdgcn_mfma_f32_16x16x32_f16((a), (b), (c), 0, 0, 0)
; template <bool SEL, bool GEN>
; DI void attn_step(const KF& kv, const int kb, const int t, const int lane, const bool selbit,
;                   const LAS float* tabh, const half8 (&q)[2][2], f32x4 (&O)[2][4], const float (&nR)[2], float (&l)[2]) {
;     ...
;       s[hp][kt] = MFMA16(kv.k[kt][0], q[hp][0], c0);
;       s[hp][kt] = MFMA16(kv.k[kt][1], q[hp][1], s[hp][kt]);
;     }
;   }
;   if (GEN) {
;     const int d0 = t - kb - fq * 4;
; #pragma unroll
;     for (int kt = 0; kt < 2; ++kt)
; #pragma unroll
;       for (int j = 0; j < 4; ++j) {
;         const int dist = d0 - (kt * 16 + j);
;         const bool bad = SEL ? (dist < 0) : ((unsigned)dist >= 512u);
;         const int ix = bad ? 130 : (dist > 128 ? 128 : dist);
; #pragma unroll
;         for (int hp = 0; hp < 2; ++hp) s[hp][kt][j] += tabh[hp * 132 + ix];
;       }
;   }
;   half8 pf[2];
; #pragma unroll
;   for (int hp = 0; hp < 2; ++hp) {
;     f32x4 p0, p1;
; #pragma unroll
;     for (int j = 0; j < 4; ++j) { p0[j] = __builtin_amdgcn_exp2f(s[hp][0][j]); p1[j] = __builtin_amdgcn_exp2f(s[hp][1][j]); }
;     l[hp] += ((p0[0] + p0[1]) + (p0[2] + p0[3])) + ((p1[0] + p1[1]) + (p1[2] + p1[3]));
;     pf[hp] = pack8(p0, p1);
;   }
; #pragma unroll
;   for (int dt = 0; dt < 4; ++dt)
; #pragma unroll
;     for (int hp = 0; hp < 2; ++hp) O[hp][dt] = MFMA16(kv.v[dt], pf[hp], O[hp][dt]);
.Lat_noga_xa1:
	v_exp_f32_e32 v198, v100
	v_exp_f32_e32 v199, v101
	v_exp_f32_e32 v200, v102
	v_exp_f32_e32 v201, v103
	v_exp_f32_e32 v202, v104
	v_exp_f32_e32 v203, v105
	v_exp_f32_e32 v204, v106
	v_exp_f32_e32 v205, v107
	v_exp_f32_e32 v206, v108
	v_exp_f32_e32 v207, v109
	v_exp_f32_e32 v208, v110
	v_exp_f32_e32 v209, v111
	v_exp_f32_e32 v210, v112
	v_exp_f32_e32 v211, v113
	v_exp_f32_e32 v212, v114
	v_exp_f32_e32 v213, v115
	v_cvt_pkrtz_f16_f32 v120, v198, v199
	v_cvt_pkrtz_f16_f32 v121, v200, v201
	v_cvt_pkrtz_f16_f32 v122, v202, v203
	v_cvt_pkrtz_f16_f32 v123, v204, v205
	v_cvt_pkrtz_f16_f32 v124, v206, v207
	v_cvt_pkrtz_f16_f32 v125, v208, v209
	v_cvt_pkrtz_f16_f32 v126, v210, v211
	v_cvt_pkrtz_f16_f32 v127, v212, v213
	s_waitcnt lgkmcnt(0)
	s_and_b32 s44, s12, 2
	s_or_b32 s44, s44, 1
	v_mfma_f32_16x16x32_f16 v[100:103], v[96:99], v[8:11], v[128:131]
	s_add_i32 s8, s45, 64
	s_min_i32 s8, s8, s14
	s_mul_i32 s8, s8, s42
	v_mfma_f32_16x16x32_f16 v[104:107], v[88:91], v[8:11], v[128:131]
	s_mov_b32 s9, 0
	v_lshl_add_u64 v[238:239], v[240:241], 0, s[8:9]
	s_add_i32 m0, s22, 0x20080
	s_nop 0
	v_mfma_f32_16x16x32_f16 v[108:111], v[96:99], v[16:19], v[132:135]
	global_load_lds_dwordx4 v[238:239], off
	s_add_i32 s45, s45, 32
	s_add_i32 s41, s41, -1
	s_add_i32 s10, s45, 0x9f
	v_mfma_f32_16x16x32_f16 v[112:115], v[88:91], v[16:19], v[132:135]
	s_cmp_gt_i32 s10, s51
	s_cselect_b32 s11, 2, 0
	s_add_i32 s10, s45, 0x1f1
	s_cmp_le_i32 s10, s51
	v_mfma_f32_16x16x32_f16 v[100:103], v[92:95], v[12:15], v[100:103]
	s_cselect_b32 s10, 2, 0
	s_and_b32 s10, s10, s4
	s_or_b32 s11, s11, s10
	v_mfma_f32_16x16x32_f16 v[104:107], v[84:87], v[12:15], v[104:107]
	s_lshr_b32 s10, s45, 6
	v_bfe_u32 v66, v244, s10, 1
	v_cmp_ne_u32_e32 vcc, 0, v66
	s_cmp_lg_u64 vcc, 0
	v_mfma_f32_16x16x32_f16 v[108:111], v[92:95], v[20:23], v[108:111]
	s_cselect_b32 s10, 1, 0
	s_lshr_b32 s9, s11, 1
	s_or_b32 s10, s10, s9
	s_cmp_le_i32 s45, s15
	v_mfma_f32_16x16x32_f16 v[112:115], v[84:87], v[20:23], v[112:115]
	s_cselect_b32 s10, s10, 0
	s_cmp_ge_i32 s45, s40
	s_cselect_b32 s10, s10, 0
	s_or_b32 s12, s11, s10
	v_mfma_f32_16x16x32_f16 v[60:63], v[80:83], v[120:123], v[60:63]
	v_add_f32_e32 v214, v214, v198
	v_add_f32_e32 v215, v215, v199
	v_mfma_f32_16x16x32_f16 v[56:59], v[76:79], v[120:123], v[56:59]
	v_add_f32_e32 v216, v216, v200
	v_add_f32_e32 v217, v217, v201
	v_mfma_f32_16x16x32_f16 v[52:55], v[72:75], v[120:123], v[52:55]
	v_add_f32_e32 v214, v214, v202
	v_add_f32_e32 v215, v215, v203
	v_mfma_f32_16x16x32_f16 v[48:51], v[68:71], v[120:123], v[48:51]
	v_add_f32_e32 v216, v216, v204
	v_add_f32_e32 v217, v217, v205
	v_mfma_f32_16x16x32_f16 v[44:47], v[80:83], v[124:127], v[44:47]
	v_add_f32_e32 v218, v218, v206
	v_add_f32_e32 v219, v219, v207
	v_mfma_f32_16x16x32_f16 v[40:43], v[76:79], v[124:127], v[40:43]
	v_add_f32_e32 v220, v220, v208
	v_add_f32_e32 v221, v221, v209
	v_mfma_f32_16x16x32_f16 v[36:39], v[72:75], v[124:127], v[36:39]
	v_add_f32_e32 v218, v218, v210
	v_add_f32_e32 v219, v219, v211
	v_mfma_f32_16x16x32_f16 v[32:35], v[68:71], v[124:127], v[32:35]
	v_add_f32_e32 v220, v220, v212
	v_add_f32_e32 v221, v221, v213
	ds_read_b128 v[80:83], v65 offset:12288
	ds_read_b128 v[76:79], v65 offset:13312
	ds_read_b128 v[72:75], v65 offset:14336
	ds_read_b128 v[68:71], v65 offset:15360
	s_cmp_lg_u32 s41, 0
	s_cbranch_scc1 .Lat_xtop2
	s_branch .Lat_xexit
.Lat_xb1:
	s_waitcnt lgkmcnt(0)
	s_and_b32 s44, s12, 2
	s_or_b32 s44, s44, 1
	v_mfma_f32_16x16x32_f16 v[100:103], v[96:99], v[8:11], v[128:131]
	s_add_i32 s8, s45, 64
	s_min_i32 s8, s8, s14
	s_mul_i32 s8, s8, s42
	v_mfma_f32_16x16x32_f16 v[104:107], v[88:91], v[8:11], v[128:131]
	s_mov_b32 s9, 0
	v_lshl_add_u64 v[238:239], v[240:241], 0, s[8:9]
	s_add_i32 m0, s22, 0x20080
	s_nop 0
	v_mfma_f32_16x16x32_f16 v[108:111], v[96:99], v[16:19], v[132:135]
	global_load_lds_dwordx4 v[238:239], off
	s_add_i32 s45, s45, 32
	s_add_i32 s41, s41, -1
	s_add_i32 s10, s45, 0x9f
	v_mfma_f32_16x16x32_f16 v[112:115], v[88:91], v[16:19], v[132:135]
	s_cmp_gt_i32 s10, s51
	s_cselect_b32 s11, 2, 0
	s_add_i32 s10, s45, 0x1f1
	s_cmp_le_i32 s10, s51
	v_mfma_f32_16x16x32_f16 v[100:103], v[92:95], v[12:15], v[100:103]
	s_cselect_b32 s10, 2, 0
	s_and_b32 s10, s10, s4
	s_or_b32 s11, s11, s10
	v_mfma_f32_16x16x32_f16 v[104:107], v[84:87], v[12:15], v[104:107]
	s_lshr_b32 s10, s45, 6
	v_bfe_u32 v66, v244, s10, 1
	v_cmp_ne_u32_e32 vcc, 0, v66
	s_cmp_lg_u64 vcc, 0
	v_mfma_f32_16x16x32_f16 v[108:111], v[92:95], v[20:23], v[108:111]
	s_cselect_b32 s10, 1, 0
	s_lshr_b32 s9, s11, 1
	s_or_b32 s10, s10, s9
	s_cmp_le_i32 s45, s15
	v_mfma_f32_16x16x32_f16 v[112:115], v[84:87], v[20:23], v[112:115]
	s_cselect_b32 s10, s10, 0
	s_cmp_ge_i32 s45, s40
	s_cselect_b32 s10, s10, 0
	s_or_b32 s12, s11, s10
	ds_read_b128 v[80:83], v65 offset:12288
	ds_read_b128 v[76:79], v65 offset:13312
	ds_read_b128 v[72:75], v65 offset:14336
	ds_read_b128 v[68:71], v65 offset:15360
	s_cmp_lg_u32 s41, 0
	s_cbranch_scc1 .Lat_xtop2
	s_branch .Lat_xexit

; #define MFMA16(a, b, c) __builtin_amdgcn_mfma_f32_16x16x32_f16((a), (b), (c), 0, 0, 0)
; template <bool SEL, bool GEN>
; DI void attn_step(const KF& kv, const int kb, const int t, const int lane, const bool selbit,
;                   const LAS float* tabh, const half8 (&q)[2][2], f32x4 (&O)[2][4], const float (&nR)[2], float (&l)[2]) {
;     ...
; #pragma unroll
;   for (int dt = 0; dt < 4; ++dt)
; #pragma unroll
;     for (int hp = 0; hp < 2; ++hp) O[hp][dt] = MFMA16(kv.v[dt], pf[hp], O[hp][dt]);
; DI void attn_phase(const Params& p, const int layer, const int wid_s) {
;     ...
;           if (kb > kmax_w || kb < lo_w) continue;
;           if (br == 1 && kb + 31 + 128 <= t0 && __ballot((selmask >> (kb >> 6)) & 1u) == 0ull) continue;
.Lat_noga_xc1:
	v_exp_f32_e32 v198, v100
	v_exp_f32_e32 v199, v101
	v_exp_f32_e32 v200, v102
	v_exp_f32_e32 v201, v103
	v_exp_f32_e32 v202, v104
	v_exp_f32_e32 v203, v105
	v_exp_f32_e32 v204, v106
	v_exp_f32_e32 v205, v107
	v_exp_f32_e32 v206, v108
	v_exp_f32_e32 v207, v109
	v_exp_f32_e32 v208, v110
	v_exp_f32_e32 v209, v111
	v_exp_f32_e32 v210, v112
	v_exp_f32_e32 v211, v113
	v_exp_f32_e32 v212, v114
	v_exp_f32_e32 v213, v115
	v_cvt_pkrtz_f16_f32 v120, v198, v199
	v_cvt_pkrtz_f16_f32 v121, v200, v201
	v_cvt_pkrtz_f16_f32 v122, v202, v203
	v_cvt_pkrtz_f16_f32 v123, v204, v205
	v_cvt_pkrtz_f16_f32 v124, v206, v207
	v_cvt_pkrtz_f16_f32 v125, v208, v209
	v_cvt_pkrtz_f16_f32 v126, v210, v211
	v_cvt_pkrtz_f16_f32 v127, v212, v213
	s_waitcnt lgkmcnt(0)
	v_mfma_f32_16x16x32_f16 v[60:63], v[80:83], v[120:123], v[60:63]
	v_add_f32_e32 v214, v214, v198
	v_add_f32_e32 v215, v215, v199
	v_add_f32_e32 v216, v216, v200
	v_add_f32_e32 v217, v217, v201
	v_add_f32_e32 v214, v214, v202
	v_mfma_f32_16x16x32_f16 v[56:59], v[76:79], v[120:123], v[56:59]
	v_add_f32_e32 v215, v215, v203
	v_add_f32_e32 v216, v216, v204
	v_add_f32_e32 v217, v217, v205
	v_add_f32_e32 v218, v218, v206
	v_add_f32_e32 v219, v219, v207
	v_add_f32_e32 v220, v220, v208
	v_mfma_f32_16x16x32_f16 v[52:55], v[72:75], v[120:123], v[52:55]
	v_add_f32_e32 v221, v221, v209
	v_add_f32_e32 v218, v218, v210
	v_add_f32_e32 v219, v219, v211
	v_add_f32_e32 v220, v220, v212
	v_add_f32_e32 v221, v221, v213
	s_add_i32 s8, s45, 64
	v_mfma_f32_16x16x32_f16 v[48:51], v[68:71], v[120:123], v[48:51]
	s_min_i32 s8, s8, s14
	s_mul_i32 s8, s8, s42
	s_mov_b32 s9, 0
	v_lshl_add_u64 v[238:239], v[240:241], 0, s[8:9]
	s_add_i32 m0, s22, 0x20080
	s_nop 0
	v_mfma_f32_16x16x32_f16 v[44:47], v[80:83], v[124:127], v[44:47]
	global_load_lds_dwordx4 v[238:239], off
	s_add_i32 s45, s45, 32
	s_add_i32 s41, s41, -1
	s_add_i32 s10, s45, 0x9f
	s_cmp_gt_i32 s10, s51
	v_mfma_f32_16x16x32_f16 v[40:43], v[76:79], v[124:127], v[40:43]
	s_cselect_b32 s11, 2, 0
	s_add_i32 s10, s45, 0x1f1
	s_cmp_le_i32 s10, s51
	s_cselect_b32 s10, 2, 0
	s_and_b32 s10, s10, s4
	s_or_b32 s11, s11, s10
	v_mfma_f32_16x16x32_f16 v[36:39], v[72:75], v[124:127], v[36:39]
	s_lshr_b32 s10, s45, 6
	v_bfe_u32 v66, v244, s10, 1
	v_cmp_ne_u32_e32 vcc, 0, v66
	s_cmp_lg_u64 vcc, 0
	s_cselect_b32 s10, 1, 0
	s_lshr_b32 s9, s11, 1
	v_mfma_f32_16x16x32_f16 v[32:35], v[68:71], v[124:127], v[32:35]
	s_or_b32 s10, s10, s9
	s_cmp_le_i32 s45, s15
	s_cselect_b32 s10, s10, 0
	s_cmp_ge_i32 s45, s40
	s_cselect_b32 s10, s10, 0
	s_or_b32 s12, s11, s10
	s_mov_b32 s44, 0
	s_cmp_lg_u32 s41, 0
	s_cbranch_scc1 .Lat_xtop2
	s_branch .Lat_xexit
.Lat_xd1:
	s_add_i32 s8, s45, 64
	s_min_i32 s8, s8, s14
	s_mul_i32 s8, s8, s42
	s_mov_b32 s9, 0
	v_lshl_add_u64 v[238:239], v[240:241], 0, s[8:9]
	s_add_i32 m0, s22, 0x20080
	s_nop 0
	global_load_lds_dwordx4 v[238:239], off
	s_add_i32 s45, s45, 32
	s_add_i32 s41, s41, -1
	s_add_i32 s10, s45, 0x9f
	s_cmp_gt_i32 s10, s51
	s_cselect_b32 s11, 2, 0
	s_add_i32 s10, s45, 0x1f1
	s_cmp_le_i32 s10, s51
	s_cselect_b32 s10, 2, 0
	s_and_b32 s10, s10, s4
	s_or_b32 s11, s11, s10
	s_lshr_b32 s10, s45, 6
	v_bfe_u32 v66, v244, s10, 1
	v_cmp_ne_u32_e32 vcc, 0, v66
	s_cmp_lg_u64 vcc, 0
	s_cselect_b32 s10, 1, 0
	s_lshr_b32 s9, s11, 1
	s_or_b32 s10, s10, s9
	s_cmp_le_i32 s45, s15
	s_cselect_b32 s10, s10, 0
	s_cmp_ge_i32 s45, s40
	s_cselect_b32 s10, s10, 0
	s_or_b32 s12, s11, s10
	s_cmp_lg_u32 s41, 0
	s_cbranch_scc1 .Lat_xtop2
	s_branch .Lat_xexit

; #define MFMA16(a, b, c) __builtin_amdgcn_mfma_f32_16x16x32_f16((a), (b), (c), 0, 0, 0)
; template <bool SEL, bool GEN>
; DI void attn_step(const KF& kv, const int kb, const int t, const int lane, const bool selbit,
;                   const LAS float* tabh, const half8 (&q)[2][2], f32x4 (&O)[2][4], const float (&nR)[2], float (&l)[2]) {
;     ...
;       s[hp][kt] = MFMA16(kv.k[kt][0], q[hp][0], c0);
;       s[hp][kt] = MFMA16(kv.k[kt][1], q[hp][1], s[hp][kt]);
;     }
;   }
;   if (GEN) {
;     const int d0 = t - kb - fq * 4;
; #pragma unroll
;     for (int kt = 0; kt < 2; ++kt)
; #pragma unroll
;       for (int j = 0; j < 4; ++j) {
;         const int dist = d0 - (kt * 16 + j);
;         const bool bad = SEL ? (dist < 0) : ((unsigned)dist >= 512u);
;         const int ix = bad ? 130 : (dist > 128 ? 128 : dist);
; #pragma unroll
;         for (int hp = 0; hp < 2; ++hp) s[hp][kt][j] += tabh[hp * 132 + ix];
;       }
;   }
;   half8 pf[2];
; #pragma unroll
;   for (int hp = 0; hp < 2; ++hp) {
;     f32x4 p0, p1;
; #pragma unroll
;     for (int j = 0; j < 4; ++j) { p0[j] = __builtin_amdgcn_exp2f(s[hp][0][j]); p1[j] = __builtin_amdgcn_exp2f(s[hp][1][j]); }
;     l[hp] += ((p0[0] + p0[1]) + (p0[2] + p0[3])) + ((p1[0] + p1[1]) + (p1[2] + p1[3]));
;     pf[hp] = pack8(p0, p1);
;   }
; #pragma unroll
;   for (int dt = 0; dt < 4; ++dt)
; #pragma unroll
;     for (int hp = 0; hp < 2; ++hp) O[hp][dt] = MFMA16(kv.v[dt], pf[hp], O[hp][dt]);
.Lat_noga_xa2:
	v_exp_f32_e32 v198, v100
	v_exp_f32_e32 v199, v101
	v_exp_f32_e32 v200, v102
	v_exp_f32_e32 v201, v103
	v_exp_f32_e32 v202, v104
	v_exp_f32_e32 v203, v105
	v_exp_f32_e32 v204, v106
	v_exp_f32_e32 v205, v107
	v_exp_f32_e32 v206, v108
	v_exp_f32_e32 v207, v109
	v_exp_f32_e32 v208, v110
	v_exp_f32_e32 v209, v111
	v_exp_f32_e32 v210, v112
	v_exp_f32_e32 v211, v113
	v_exp_f32_e32 v212, v114
	v_exp_f32_e32 v213, v115
	v_cvt_pkrtz_f16_f32 v120, v198, v199
	v_cvt_pkrtz_f16_f32 v121, v200, v201
	v_cvt_pkrtz_f16_f32 v122, v202, v203
	v_cvt_pkrtz_f16_f32 v123, v204, v205
	v_cvt_pkrtz_f16_f32 v124, v206, v207
	v_cvt_pkrtz_f16_f32 v125, v208, v209
	v_cvt_pkrtz_f16_f32 v126, v210, v211
	v_cvt_pkrtz_f16_f32 v127, v212, v213
	s_waitcnt lgkmcnt(0)
	s_and_b32 s44, s12, 2
	s_or_b32 s44, s44, 1
	v_mfma_f32_16x16x32_f16 v[100:103], v[96:99], v[8:11], v[128:131]
	s_add_i32 s8, s45, 64
	s_min_i32 s8, s8, s14
	s_mul_i32 s8, s8, s42
	v_mfma_f32_16x16x32_f16 v[104:107], v[88:91], v[8:11], v[128:131]
	s_mov_b32 s9, 0
	v_lshl_add_u64 v[238:239], v[240:241], 0, s[8:9]
	s_add_i32 m0, s22, 0x19880
	s_nop 0
	v_mfma_f32_16x16x32_f16 v[108:111], v[96:99], v[16:19], v[132:135]
	global_load_lds_dwordx4 v[238:239], off
	s_add_i32 s45, s45, 32
	s_add_i32 s41, s41, -1
	s_add_i32 s10, s45, 0x9f
	v_mfma_f32_16x16x32_f16 v[112:115], v[88:91], v[16:19], v[132:135]
	s_cmp_gt_i32 s10, s51
	s_cselect_b32 s11, 2, 0
	s_add_i32 s10, s45, 0x1f1
	s_cmp_le_i32 s10, s51
	v_mfma_f32_16x16x32_f16 v[100:103], v[92:95], v[12:15], v[100:103]
	s_cselect_b32 s10, 2, 0
	s_and_b32 s10, s10, s4
	s_or_b32 s11, s11, s10
	v_mfma_f32_16x16x32_f16 v[104:107], v[84:87], v[12:15], v[104:107]
	s_lshr_b32 s10, s45, 6
	v_bfe_u32 v66, v244, s10, 1
	v_cmp_ne_u32_e32 vcc, 0, v66
	s_cmp_lg_u64 vcc, 0
	v_mfma_f32_16x16x32_f16 v[108:111], v[92:95], v[20:23], v[108:111]
	s_cselect_b32 s10, 1, 0
	s_lshr_b32 s9, s11, 1
	s_or_b32 s10, s10, s9
	s_cmp_le_i32 s45, s15
	v_mfma_f32_16x16x32_f16 v[112:115], v[84:87], v[20:23], v[112:115]
	s_cselect_b32 s10, s10, 0
	s_cmp_ge_i32 s45, s40
	s_cselect_b32 s10, s10, 0
	s_or_b32 s12, s11, s10
	v_mfma_f32_16x16x32_f16 v[60:63], v[80:83], v[120:123], v[60:63]
	v_add_f32_e32 v214, v214, v198
	v_add_f32_e32 v215, v215, v199
	v_mfma_f32_16x16x32_f16 v[56:59], v[76:79], v[120:123], v[56:59]
	v_add_f32_e32 v216, v216, v200
	v_add_f32_e32 v217, v217, v201
	v_mfma_f32_16x16x32_f16 v[52:55], v[72:75], v[120:123], v[52:55]
	v_add_f32_e32 v214, v214, v202
	v_add_f32_e32 v215, v215, v203
	v_mfma_f32_16x16x32_f16 v[48:51], v[68:71], v[120:123], v[48:51]
	v_add_f32_e32 v216, v216, v204
	v_add_f32_e32 v217, v217, v205
	v_mfma_f32_16x16x32_f16 v[44:47], v[80:83], v[124:127], v[44:47]
	v_add_f32_e32 v218, v218, v206
	v_add_f32_e32 v219, v219, v207
	v_mfma_f32_16x16x32_f16 v[40:43], v[76:79], v[124:127], v[40:43]
	v_add_f32_e32 v220, v220, v208
	v_add_f32_e32 v221, v221, v209
	v_mfma_f32_16x16x32_f16 v[36:39], v[72:75], v[124:127], v[36:39]
	v_add_f32_e32 v218, v218, v210
	v_add_f32_e32 v219, v219, v211
	v_mfma_f32_16x16x32_f16 v[32:35], v[68:71], v[124:127], v[32:35]
	v_add_f32_e32 v220, v220, v212
	v_add_f32_e32 v221, v221, v213
	ds_read_b128 v[80:83], v65 offset:20480
	ds_read_b128 v[76:79], v65 offset:21504
	ds_read_b128 v[72:75], v65 offset:22528
	ds_read_b128 v[68:71], v65 offset:23552
	s_cmp_lg_u32 s41, 0
	s_cbranch_scc1 .Lat_xtop3
	s_branch .Lat_xexit
.Lat_xb2:
	s_waitcnt lgkmcnt(0)
	s_and_b32 s44, s12, 2
	s_or_b32 s44, s44, 1
	v_mfma_f32_16x16x32_f16 v[100:103], v[96:99], v[8:11], v[128:131]
	s_add_i32 s8, s45, 64
	s_min_i32 s8, s8, s14
	s_mul_i32 s8, s8, s42
	v_mfma_f32_16x16x32_f16 v[104:107], v[88:91], v[8:11], v[128:131]
	s_mov_b32 s9, 0
	v_lshl_add_u64 v[238:239], v[240:241], 0, s[8:9]
	s_add_i32 m0, s22, 0x19880
	s_nop 0
	v_mfma_f32_16x16x32_f16 v[108:111], v[96:99], v[16:19], v[132:135]
	global_load_lds_dwordx4 v[238:239], off
	s_add_i32 s45, s45, 32
	s_add_i32 s41, s41, -1
	s_add_i32 s10, s45, 0x9f
	v_mfma_f32_16x16x32_f16 v[112:115], v[88:91], v[16:19], v[132:135]
	s_cmp_gt_i32 s10, s51
	s_cselect_b32 s11, 2, 0
	s_add_i32 s10, s45, 0x1f1
	s_cmp_le_i32 s10, s51
	v_mfma_f32_16x16x32_f16 v[100:103], v[92:95], v[12:15], v[100:103]
	s_cselect_b32 s10, 2, 0
	s_and_b32 s10, s10, s4
	s_or_b32 s11, s11, s10
	v_mfma_f32_16x16x32_f16 v[104:107], v[84:87], v[12:15], v[104:107]
	s_lshr_b32 s10, s45, 6
	v_bfe_u32 v66, v244, s10, 1
	v_cmp_ne_u32_e32 vcc, 0, v66
	s_cmp_lg_u64 vcc, 0
	v_mfma_f32_16x16x32_f16 v[108:111], v[92:95], v[20:23], v[108:111]
	s_cselect_b32 s10, 1, 0
	s_lshr_b32 s9, s11, 1
	s_or_b32 s10, s10, s9
	s_cmp_le_i32 s45, s15
	v_mfma_f32_16x16x32_f16 v[112:115], v[84:87], v[20:23], v[112:115]
	s_cselect_b32 s10, s10, 0
	s_cmp_ge_i32 s45, s40
	s_cselect_b32 s10, s10, 0
	s_or_b32 s12, s11, s10
	ds_read_b128 v[80:83], v65 offset:20480
	ds_read_b128 v[76:79], v65 offset:21504
	ds_read_b128 v[72:75], v65 offset:22528
	ds_read_b128 v[68:71], v65 offset:23552
	s_cmp_lg_u32 s41, 0
	s_cbranch_scc1 .Lat_xtop3
	s_branch .Lat_xexit

; #define MFMA16(a, b, c) __builtin_amdgcn_mfma_f32_16x16x32_f16((a), (b), (c), 0, 0, 0)
; #define LAS __attribute__((address_space(3)))
; template <bool SEL, bool GEN>
; DI void attn_step(const KF& kv, const int kb, const int t, const int lane, const bool selbit,
;                   const LAS float* tabh, const half8 (&q)[2][2], f32x4 (&O)[2][4], const float (&nR)[2], float (&l)[2]) {
;     ...
;     for (int j = 0; j < 4; ++j) { p0[j] = __builtin_amdgcn_exp2f(s[hp][0][j]); p1[j] = __builtin_amdgcn_exp2f(s[hp][1][j]); }
;     l[hp] += ((p0[0] + p0[1]) + (p0[2] + p0[3])) + ((p1[0] + p1[1]) + (p1[2] + p1[3]));
;     pf[hp] = pack8(p0, p1);
;   }
; #pragma unroll
;   for (int dt = 0; dt < 4; ++dt)
; #pragma unroll
;     for (int hp = 0; hp < 2; ++hp) O[hp][dt] = MFMA16(kv.v[dt], pf[hp], O[hp][dt]);
; DI void attn_phase(const Params& p, const int layer, const int wid_s) {
;     ...
;         asm volatile("s_waitcnt vmcnt(0)" ::: "memory");
;         __syncthreads();
;         RING_ISSUE(0); RING_ISSUE(1);
; #pragma unroll 1
;         for (int si = 0; si < nsteps; ++si) {
;           asm volatile("s_waitcnt vmcnt(1) lgkmcnt(0)" ::: "memory");
;           __builtin_amdgcn_s_barrier();
;           asm volatile("" ::: "memory");
;           RING_ISSUE(si + 2);
;           const int kb = kb0 + si * 32;
;           if (kb > kmax_w || kb < lo_w) continue;
;           if (br == 1 && kb + 31 + 128 <= t0 && __ballot((selmask >> (kb >> 6)) & 1u) == 0ull) continue;
;           LAS unsigned char* slotp = ring + (si % 3) * 8192;
;           KF kv;
; #pragma unroll
;           for (int kt = 0; kt < 2; ++kt)
; #pragma unroll
;             for (int ks = 0; ks < 2; ++ks) kv.k[kt][ks] = *(const LAS half8*)(slotp + kread[kt][ks]);
; #pragma unroll
;           for (int dt = 0; dt < 4; ++dt) kv.v[dt] = *(const LAS half8*)(slotp + vread[dt]);
;           if (br == 1) {
;             const bool bit = (selmask >> (kb >> 6)) & 1u;
;             if (kb + 31 + 128 <= t0) attn_step<true, false>(kv, kb, t, lane, bit, tabh, q, O, nRs, l);
;             else attn_step<true, true>(kv, kb, t, lane, bit, tabh, q, O, nRs, l);
;           } else {
;             const bool gen = (kb + 31 + 128 > t0) || (kb + 512 <= t0 + 15);
.Lat_noga_xc2:
	v_exp_f32_e32 v198, v100
	v_exp_f32_e32 v199, v101
	v_exp_f32_e32 v200, v102
	v_exp_f32_e32 v201, v103
	v_exp_f32_e32 v202, v104
	v_exp_f32_e32 v203, v105
	v_exp_f32_e32 v204, v106
	v_exp_f32_e32 v205, v107
	v_exp_f32_e32 v206, v108
	v_exp_f32_e32 v207, v109
	v_exp_f32_e32 v208, v110
	v_exp_f32_e32 v209, v111
	v_exp_f32_e32 v210, v112
	v_exp_f32_e32 v211, v113
	v_exp_f32_e32 v212, v114
	v_exp_f32_e32 v213, v115
	v_cvt_pkrtz_f16_f32 v120, v198, v199
	v_cvt_pkrtz_f16_f32 v121, v200, v201
	v_cvt_pkrtz_f16_f32 v122, v202, v203
	v_cvt_pkrtz_f16_f32 v123, v204, v205
	v_cvt_pkrtz_f16_f32 v124, v206, v207
	v_cvt_pkrtz_f16_f32 v125, v208, v209
	v_cvt_pkrtz_f16_f32 v126, v210, v211
	v_cvt_pkrtz_f16_f32 v127, v212, v213
	s_waitcnt lgkmcnt(0)
	v_mfma_f32_16x16x32_f16 v[60:63], v[80:83], v[120:123], v[60:63]
	v_add_f32_e32 v214, v214, v198
	v_add_f32_e32 v215, v215, v199
	v_add_f32_e32 v216, v216, v200
	v_add_f32_e32 v217, v217, v201
	v_add_f32_e32 v214, v214, v202
	v_mfma_f32_16x16x32_f16 v[56:59], v[76:79], v[120:123], v[56:59]
	v_add_f32_e32 v215, v215, v203
	v_add_f32_e32 v216, v216, v204
	v_add_f32_e32 v217, v217, v205
	v_add_f32_e32 v218, v218, v206
	v_add_f32_e32 v219, v219, v207
	v_add_f32_e32 v220, v220, v208
	v_mfma_f32_16x16x32_f16 v[52:55], v[72:75], v[120:123], v[52:55]
	v_add_f32_e32 v221, v221, v209
	v_add_f32_e32 v218, v218, v210
	v_add_f32_e32 v219, v219, v211
	v_add_f32_e32 v220, v220, v212
	v_add_f32_e32 v221, v221, v213
	s_add_i32 s8, s45, 64
	v_mfma_f32_16x16x32_f16 v[48:51], v[68:71], v[120:123], v[48:51]
	s_min_i32 s8, s8, s14
	s_mul_i32 s8, s8, s42
	s_mov_b32 s9, 0
	v_lshl_add_u64 v[238:239], v[240:241], 0, s[8:9]
	s_add_i32 m0, s22, 0x19880
	s_nop 0
	v_mfma_f32_16x16x32_f16 v[44:47], v[80:83], v[124:127], v[44:47]
	global_load_lds_dwordx4 v[238:239], off
	s_add_i32 s45, s45, 32
	s_add_i32 s41, s41, -1
	s_add_i32 s10, s45, 0x9f
	s_cmp_gt_i32 s10, s51
	v_mfma_f32_16x16x32_f16 v[40:43], v[76:79], v[124:127], v[40:43]
	s_cselect_b32 s11, 2, 0
	s_add_i32 s10, s45, 0x1f1
	s_cmp_le_i32 s10, s51
	s_cselect_b32 s10, 2, 0
	s_and_b32 s10, s10, s4
	s_or_b32 s11, s11, s10
	v_mfma_f32_16x16x32_f16 v[36:39], v[72:75], v[124:127], v[36:39]
	s_lshr_b32 s10, s45, 6
	v_bfe_u32 v66, v244, s10, 1
	v_cmp_ne_u32_e32 vcc, 0, v66
	s_cmp_lg_u64 vcc, 0
	s_cselect_b32 s10, 1, 0
	s_lshr_b32 s9, s11, 1
	v_mfma_f32_16x16x32_f16 v[32:35], v[68:71], v[124:127], v[32:35]
	s_or_b32 s10, s10, s9
	s_cmp_le_i32 s45, s15
	s_cselect_b32 s10, s10, 0
	s_cmp_ge_i32 s45, s40
	s_cselect_b32 s10, s10, 0
	s_or_b32 s12, s11, s10
	s_mov_b32 s44, 0
	s_cmp_lg_u32 s41, 0
	s_cbranch_scc1 .Lat_xtop3
	s_branch .Lat_xexit
.Lat_xd2:
	s_add_i32 s8, s45, 64
	s_min_i32 s8, s8, s14
	s_mul_i32 s8, s8, s42
	s_mov_b32 s9, 0
	v_lshl_add_u64 v[238:239], v[240:241], 0, s[8:9]
	s_add_i32 m0, s22, 0x19880
	s_nop 0
	global_load_lds_dwordx4 v[238:239], off
	s_add_i32 s45, s45, 32
	s_add_i32 s41, s41, -1
	s_add_i32 s10, s45, 0x9f
	s_cmp_gt_i32 s10, s51
	s_cselect_b32 s11, 2, 0
	s_add_i32 s10, s45, 0x1f1
	s_cmp_le_i32 s10, s51
	s_cselect_b32 s10, 2, 0
	s_and_b32 s10, s10, s4
	s_or_b32 s11, s11, s10
	s_lshr_b32 s10, s45, 6
	v_bfe_u32 v66, v244, s10, 1
	v_cmp_ne_u32_e32 vcc, 0, v66
	s_cmp_lg_u64 vcc, 0
	s_cselect_b32 s10, 1, 0
	s_lshr_b32 s9, s11, 1
	s_or_b32 s10, s10, s9
	s_cmp_le_i32 s45, s15
	s_cselect_b32 s10, s10, 0
	s_cmp_ge_i32 s45, s40
	s_cselect_b32 s10, s10, 0
	s_or_b32 s12, s11, s10
	s_cmp_lg_u32 s41, 0
	s_cbranch_scc1 .Lat_xtop3
	s_branch .Lat_xexit

; template <bool SEL, bool GEN>
; DI void attn_step(const KF& kv, const int kb, const int t, const int lane, const bool selbit,
;                   const LAS float* tabh, const half8 (&q)[2][2], f32x4 (&O)[2][4], const float (&nR)[2], float (&l)[2]) {
;     ...
;   for (int hp = 0; hp < 2; ++hp) {
;     float nm = nR[hp];
;     if (SEL) nm = selbit ? nm : MASKV;
;     const f32x4 c0 = {nm, nm, nm, nm};
; #pragma unroll
;     for (int kt = 0; kt < 2; ++kt) {
;       s[hp][kt] = MFMA16(kv.k[kt][0], q[hp][0], c0);
;       s[hp][kt] = MFMA16(kv.k[kt][1], q[hp][1], s[hp][kt]);
;     }
;   }
;   if (GEN) {
;     const int d0 = t - kb - fq * 4;
; #pragma unroll
;     for (int kt = 0; kt < 2; ++kt)
; #pragma unroll
;       for (int j = 0; j < 4; ++j) {
;         const int dist = d0 - (kt * 16 + j);
;         const bool bad = SEL ? (dist < 0) : ((unsigned)dist >= 512u);
;         const int ix = bad ? 130 : (dist > 128 ? 128 : dist);
; #pragma unroll
;         for (int hp = 0; hp < 2; ++hp) s[hp][kt][j] += tabh[hp * 132 + ix];
;       }
;   }
;   half8 pf[2];
; #pragma unroll
;   for (int hp = 0; hp < 2; ++hp) {
;     f32x4 p0, p1;
; #pragma unroll
;     for (int j = 0; j < 4; ++j) { p0[j] = __builtin_amdgcn_exp2f(s[hp][0][j]); p1[j] = __builtin_amdgcn_exp2f(s[hp][1][j]); }
;     l[hp] += ((p0[0] + p0[1]) + (p0[2] + p0[3])) + ((p1[0] + p1[1]) + (p1[2] + p1[3]));
;     pf[hp] = pack8(p0, p1);
;   }
; #pragma unroll
;   for (int dt = 0; dt < 4; ++dt)
; #pragma unroll
;     for (int hp = 0; hp < 2; ++hp) O[hp][dt] = MFMA16(kv.v[dt], pf[hp], O[hp][dt]);
; DI void attn_phase(const Params& p, const int layer, const int wid_s) {
;     ...
;         asm volatile("s_waitcnt vmcnt(0)" ::: "memory");
;         __syncthreads();
;         RING_ISSUE(0); RING_ISSUE(1);
; #pragma unroll 1
;         for (int si = 0; si < nsteps; ++si) {
;           asm volatile("s_waitcnt vmcnt(1) lgkmcnt(0)" ::: "memory");
;           __builtin_amdgcn_s_barrier();
;           asm volatile("" ::: "memory");
;           RING_ISSUE(si + 2);
;           const int kb = kb0 + si * 32;
;           if (kb > kmax_w || kb < lo_w) continue;
;           if (br == 1 && kb + 31 + 128 <= t0 && __ballot((selmask >> (kb >> 6)) & 1u) == 0ull) continue;
;           LAS unsigned char* slotp = ring + (si % 3) * 8192;
;           KF kv;
; #pragma unroll
;           for (int kt = 0; kt < 2; ++kt)
; #pragma unroll
.Lat_noga_xa3:
	v_exp_f32_e32 v198, v100
	v_exp_f32_e32 v199, v101
	v_exp_f32_e32 v200, v102
	v_exp_f32_e32 v201, v103
	v_exp_f32_e32 v202, v104
	v_exp_f32_e32 v203, v105
	v_exp_f32_e32 v204, v106
	v_exp_f32_e32 v205, v107
	v_exp_f32_e32 v206, v108
	v_exp_f32_e32 v207, v109
	v_exp_f32_e32 v208, v110
	v_exp_f32_e32 v209, v111
	v_exp_f32_e32 v210, v112
	v_exp_f32_e32 v211, v113
	v_exp_f32_e32 v212, v114
	v_exp_f32_e32 v213, v115
	v_cvt_pkrtz_f16_f32 v120, v198, v199
	v_cvt_pkrtz_f16_f32 v121, v200, v201
	v_cvt_pkrtz_f16_f32 v122, v202, v203
	v_cvt_pkrtz_f16_f32 v123, v204, v205
	v_cvt_pkrtz_f16_f32 v124, v206, v207
	v_cvt_pkrtz_f16_f32 v125, v208, v209
	v_cvt_pkrtz_f16_f32 v126, v210, v211
	v_cvt_pkrtz_f16_f32 v127, v212, v213
	s_waitcnt lgkmcnt(0)
	s_and_b32 s44, s12, 2
	s_or_b32 s44, s44, 1
	v_mfma_f32_16x16x32_f16 v[100:103], v[96:99], v[8:11], v[128:131]
	s_add_i32 s8, s45, 64
	s_min_i32 s8, s8, s14
	s_mul_i32 s8, s8, s42
	v_mfma_f32_16x16x32_f16 v[104:107], v[88:91], v[8:11], v[128:131]
	s_mov_b32 s9, 0
	v_lshl_add_u64 v[238:239], v[240:241], 0, s[8:9]
	s_add_i32 m0, s22, 0x1b880
	s_nop 0
	v_mfma_f32_16x16x32_f16 v[108:111], v[96:99], v[16:19], v[132:135]
	global_load_lds_dwordx4 v[238:239], off
	s_add_i32 s45, s45, 32
	s_add_i32 s41, s41, -1
	s_add_i32 s10, s45, 0x9f
	v_mfma_f32_16x16x32_f16 v[112:115], v[88:91], v[16:19], v[132:135]
	s_cmp_gt_i32 s10, s51
	s_cselect_b32 s11, 2, 0
	s_add_i32 s10, s45, 0x1f1
	s_cmp_le_i32 s10, s51
	v_mfma_f32_16x16x32_f16 v[100:103], v[92:95], v[12:15], v[100:103]
	s_cselect_b32 s10, 2, 0
	s_and_b32 s10, s10, s4
	s_or_b32 s11, s11, s10
	v_mfma_f32_16x16x32_f16 v[104:107], v[84:87], v[12:15], v[104:107]
	s_lshr_b32 s10, s45, 6
	v_bfe_u32 v66, v244, s10, 1
	v_cmp_ne_u32_e32 vcc, 0, v66
	s_cmp_lg_u64 vcc, 0
	v_mfma_f32_16x16x32_f16 v[108:111], v[92:95], v[20:23], v[108:111]
	s_cselect_b32 s10, 1, 0
	s_lshr_b32 s9, s11, 1
	s_or_b32 s10, s10, s9
	s_cmp_le_i32 s45, s15
	v_mfma_f32_16x16x32_f16 v[112:115], v[84:87], v[20:23], v[112:115]
	s_cselect_b32 s10, s10, 0
	s_cmp_ge_i32 s45, s40
	s_cselect_b32 s10, s10, 0
	s_or_b32 s12, s11, s10
	v_mfma_f32_16x16x32_f16 v[60:63], v[80:83], v[120:123], v[60:63]
	v_add_f32_e32 v214, v214, v198
	v_add_f32_e32 v215, v215, v199
	v_mfma_f32_16x16x32_f16 v[56:59], v[76:79], v[120:123], v[56:59]
	v_add_f32_e32 v216, v216, v200
	v_add_f32_e32 v217, v217, v201
	v_mfma_f32_16x16x32_f16 v[52:55], v[72:75], v[120:123], v[52:55]
	v_add_f32_e32 v214, v214, v202
	v_add_f32_e32 v215, v215, v203
	v_mfma_f32_16x16x32_f16 v[48:51], v[68:71], v[120:123], v[48:51]
	v_add_f32_e32 v216, v216, v204
	v_add_f32_e32 v217, v217, v205
	v_mfma_f32_16x16x32_f16 v[44:47], v[80:83], v[124:127], v[44:47]
	v_add_f32_e32 v218, v218, v206
	v_add_f32_e32 v219, v219, v207
	v_mfma_f32_16x16x32_f16 v[40:43], v[76:79], v[124:127], v[40:43]
	v_add_f32_e32 v220, v220, v208
	v_add_f32_e32 v221, v221, v209
	v_mfma_f32_16x16x32_f16 v[36:39], v[72:75], v[124:127], v[36:39]
	v_add_f32_e32 v218, v218, v210
	v_add_f32_e32 v219, v219, v211
	v_mfma_f32_16x16x32_f16 v[32:35], v[68:71], v[124:127], v[32:35]
	v_add_f32_e32 v220, v220, v212
	v_add_f32_e32 v221, v221, v213
	ds_read_b128 v[80:83], v65 offset:30720
	ds_read_b128 v[76:79], v65 offset:31744
	ds_read_b128 v[72:75], v65 offset:32768
	ds_read_b128 v[68:71], v65 offset:33792
	s_cmp_lg_u32 s41, 0
	s_cbranch_scc1 .Lat_xtop
	s_branch .Lat_xexit
.Lat_xb3:
	s_waitcnt lgkmcnt(0)
	s_and_b32 s44, s12, 2
	s_or_b32 s44, s44, 1
	v_mfma_f32_16x16x32_f16 v[100:103], v[96:99], v[8:11], v[128:131]
	s_add_i32 s8, s45, 64
	s_min_i32 s8, s8, s14
	s_mul_i32 s8, s8, s42
	v_mfma_f32_16x16x32_f16 v[104:107], v[88:91], v[8:11], v[128:131]
	s_mov_b32 s9, 0
	v_lshl_add_u64 v[238:239], v[240:241], 0, s[8:9]
	s_add_i32 m0, s22, 0x1b880
	s_nop 0
	v_mfma_f32_16x16x32_f16 v[108:111], v[96:99], v[16:19], v[132:135]
	global_load_lds_dwordx4 v[238:239], off
	s_add_i32 s45, s45, 32
	s_add_i32 s41, s41, -1
	s_add_i32 s10, s45, 0x9f
	v_mfma_f32_16x16x32_f16 v[112:115], v[88:91], v[16:19], v[132:135]
	s_cmp_gt_i32 s10, s51
	s_cselect_b32 s11, 2, 0
	s_add_i32 s10, s45, 0x1f1
	s_cmp_le_i32 s10, s51
	v_mfma_f32_16x16x32_f16 v[100:103], v[92:95], v[12:15], v[100:103]
	s_cselect_b32 s10, 2, 0
	s_and_b32 s10, s10, s4
	s_or_b32 s11, s11, s10
	v_mfma_f32_16x16x32_f16 v[104:107], v[84:87], v[12:15], v[104:107]
	s_lshr_b32 s10, s45, 6
	v_bfe_u32 v66, v244, s10, 1
	v_cmp_ne_u32_e32 vcc, 0, v66
	s_cmp_lg_u64 vcc, 0
	v_mfma_f32_16x16x32_f16 v[108:111], v[92:95], v[20:23], v[108:111]
	s_cselect_b32 s10, 1, 0
	s_lshr_b32 s9, s11, 1
	s_or_b32 s10, s10, s9
	s_cmp_le_i32 s45, s15
	v_mfma_f32_16x16x32_f16 v[112:115], v[84:87], v[20:23], v[112:115]
	s_cselect_b32 s10, s10, 0
	s_cmp_ge_i32 s45, s40
	s_cselect_b32 s10, s10, 0
	s_or_b32 s12, s11, s10
	ds_read_b128 v[80:83], v65 offset:30720
	ds_read_b128 v[76:79], v65 offset:31744
	ds_read_b128 v[72:75], v65 offset:32768
	ds_read_b128 v[68:71], v65 offset:33792
	s_cmp_lg_u32 s41, 0
	s_cbranch_scc1 .Lat_xtop
	s_branch .Lat_xexit

; #define MFMA16(a, b, c) __builtin_amdgcn_mfma_f32_16x16x32_f16((a), (b), (c), 0, 0, 0)
; #define LAS __attribute__((address_space(3)))
; template <bool SEL, bool GEN>
; DI void attn_step(const KF& kv, const int kb, const int t, const int lane, const bool selbit,
;                   const LAS float* tabh, const half8 (&q)[2][2], f32x4 (&O)[2][4], const float (&nR)[2], float (&l)[2]) {
;     ...
;     for (int j = 0; j < 4; ++j) { p0[j] = __builtin_amdgcn_exp2f(s[hp][0][j]); p1[j] = __builtin_amdgcn_exp2f(s[hp][1][j]); }
;     l[hp] += ((p0[0] + p0[1]) + (p0[2] + p0[3])) + ((p1[0] + p1[1]) + (p1[2] + p1[3]));
;     pf[hp] = pack8(p0, p1);
;   }
; #pragma unroll
;   for (int dt = 0; dt < 4; ++dt)
; #pragma unroll
;     for (int hp = 0; hp < 2; ++hp) O[hp][dt] = MFMA16(kv.v[dt], pf[hp], O[hp][dt]);
; DI void attn_phase(const Params& p, const int layer, const int wid_s) {
;     ...
;         asm volatile("s_waitcnt vmcnt(0)" ::: "memory");
;         __syncthreads();
;         RING_ISSUE(0); RING_ISSUE(1);
; #pragma unroll 1
;         for (int si = 0; si < nsteps; ++si) {
;           asm volatile("s_waitcnt vmcnt(1) lgkmcnt(0)" ::: "memory");
;           __builtin_amdgcn_s_barrier();
;           asm volatile("" ::: "memory");
;           RING_ISSUE(si + 2);
;           const int kb = kb0 + si * 32;
;           if (kb > kmax_w || kb < lo_w) continue;
;           if (br == 1 && kb + 31 + 128 <= t0 && __ballot((selmask >> (kb >> 6)) & 1u) == 0ull) continue;
;           LAS unsigned char* slotp = ring + (si % 3) * 8192;
;           KF kv;
; #pragma unroll
;           for (int kt = 0; kt < 2; ++kt)
; #pragma unroll
;             for (int ks = 0; ks < 2; ++ks) kv.k[kt][ks] = *(const LAS half8*)(slotp + kread[kt][ks]);
; #pragma unroll
;           for (int dt = 0; dt < 4; ++dt) kv.v[dt] = *(const LAS half8*)(slotp + vread[dt]);
;           if (br == 1) {
;             const bool bit = (selmask >> (kb >> 6)) & 1u;
;             if (kb + 31 + 128 <= t0) attn_step<true, false>(kv, kb, t, lane, bit, tabh, q, O, nRs, l);
;             else attn_step<true, true>(kv, kb, t, lane, bit, tabh, q, O, nRs, l);
;           } else {
;             const bool gen = (kb + 31 + 128 > t0) || (kb + 512 <= t0 + 15);
.Lat_noga_xc3:
	v_exp_f32_e32 v198, v100
	v_exp_f32_e32 v199, v101
	v_exp_f32_e32 v200, v102
	v_exp_f32_e32 v201, v103
	v_exp_f32_e32 v202, v104
	v_exp_f32_e32 v203, v105
	v_exp_f32_e32 v204, v106
	v_exp_f32_e32 v205, v107
	v_exp_f32_e32 v206, v108
	v_exp_f32_e32 v207, v109
	v_exp_f32_e32 v208, v110
	v_exp_f32_e32 v209, v111
	v_exp_f32_e32 v210, v112
	v_exp_f32_e32 v211, v113
	v_exp_f32_e32 v212, v114
	v_exp_f32_e32 v213, v115
	v_cvt_pkrtz_f16_f32 v120, v198, v199
	v_cvt_pkrtz_f16_f32 v121, v200, v201
	v_cvt_pkrtz_f16_f32 v122, v202, v203
	v_cvt_pkrtz_f16_f32 v123, v204, v205
	v_cvt_pkrtz_f16_f32 v124, v206, v207
	v_cvt_pkrtz_f16_f32 v125, v208, v209
	v_cvt_pkrtz_f16_f32 v126, v210, v211
	v_cvt_pkrtz_f16_f32 v127, v212, v213
	s_waitcnt lgkmcnt(0)
	v_mfma_f32_16x16x32_f16 v[60:63], v[80:83], v[120:123], v[60:63]
	v_add_f32_e32 v214, v214, v198
	v_add_f32_e32 v215, v215, v199
	v_add_f32_e32 v216, v216, v200
	v_add_f32_e32 v217, v217, v201
	v_add_f32_e32 v214, v214, v202
	v_mfma_f32_16x16x32_f16 v[56:59], v[76:79], v[120:123], v[56:59]
	v_add_f32_e32 v215, v215, v203
	v_add_f32_e32 v216, v216, v204
	v_add_f32_e32 v217, v217, v205
	v_add_f32_e32 v218, v218, v206
	v_add_f32_e32 v219, v219, v207
	v_add_f32_e32 v220, v220, v208
	v_mfma_f32_16x16x32_f16 v[52:55], v[72:75], v[120:123], v[52:55]
	v_add_f32_e32 v221, v221, v209
	v_add_f32_e32 v218, v218, v210
	v_add_f32_e32 v219, v219, v211
	v_add_f32_e32 v220, v220, v212
	v_add_f32_e32 v221, v221, v213
	s_add_i32 s8, s45, 64
	v_mfma_f32_16x16x32_f16 v[48:51], v[68:71], v[120:123], v[48:51]
	s_min_i32 s8, s8, s14
	s_mul_i32 s8, s8, s42
	s_mov_b32 s9, 0
	v_lshl_add_u64 v[238:239], v[240:241], 0, s[8:9]
	s_add_i32 m0, s22, 0x1b880
	s_nop 0
	v_mfma_f32_16x16x32_f16 v[44:47], v[80:83], v[124:127], v[44:47]
	global_load_lds_dwordx4 v[238:239], off
	s_add_i32 s45, s45, 32
	s_add_i32 s41, s41, -1
	s_add_i32 s10, s45, 0x9f
	s_cmp_gt_i32 s10, s51
	v_mfma_f32_16x16x32_f16 v[40:43], v[76:79], v[124:127], v[40:43]
	s_cselect_b32 s11, 2, 0
	s_add_i32 s10, s45, 0x1f1
	s_cmp_le_i32 s10, s51
	s_cselect_b32 s10, 2, 0
	s_and_b32 s10, s10, s4
	s_or_b32 s11, s11, s10
	v_mfma_f32_16x16x32_f16 v[36:39], v[72:75], v[124:127], v[36:39]
	s_lshr_b32 s10, s45, 6
	v_bfe_u32 v66, v244, s10, 1
	v_cmp_ne_u32_e32 vcc, 0, v66
	s_cmp_lg_u64 vcc, 0
	s_cselect_b32 s10, 1, 0
	s_lshr_b32 s9, s11, 1
	v_mfma_f32_16x16x32_f16 v[32:35], v[68:71], v[124:127], v[32:35]
	s_or_b32 s10, s10, s9
	s_cmp_le_i32 s45, s15
	s_cselect_b32 s10, s10, 0
	s_cmp_ge_i32 s45, s40
	s_cselect_b32 s10, s10, 0
	s_or_b32 s12, s11, s10
	s_mov_b32 s44, 0
	s_cmp_lg_u32 s41, 0
	s_cbranch_scc1 .Lat_xtop
	s_branch .Lat_xexit
.Lat_xd3:
	s_add_i32 s8, s45, 64
	s_min_i32 s8, s8, s14
	s_mul_i32 s8, s8, s42
	s_mov_b32 s9, 0
	v_lshl_add_u64 v[238:239], v[240:241], 0, s[8:9]
	s_add_i32 m0, s22, 0x1b880
	s_nop 0
	global_load_lds_dwordx4 v[238:239], off
	s_add_i32 s45, s45, 32
	s_add_i32 s41, s41, -1
	s_add_i32 s10, s45, 0x9f
	s_cmp_gt_i32 s10, s51
	s_cselect_b32 s11, 2, 0
	s_add_i32 s10, s45, 0x1f1
	s_cmp_le_i32 s10, s51
	s_cselect_b32 s10, 2, 0
	s_and_b32 s10, s10, s4
	s_or_b32 s11, s11, s10
	s_lshr_b32 s10, s45, 6
	v_bfe_u32 v66, v244, s10, 1
	v_cmp_ne_u32_e32 vcc, 0, v66
	s_cmp_lg_u64 vcc, 0
	s_cselect_b32 s10, 1, 0
	s_lshr_b32 s9, s11, 1
	s_or_b32 s10, s10, s9
	s_cmp_le_i32 s45, s15
	s_cselect_b32 s10, s10, 0
	s_cmp_ge_i32 s45, s40
	s_cselect_b32 s10, s10, 0
	s_or_b32 s12, s11, s10
	s_cmp_lg_u32 s41, 0
	s_cbranch_scc1 .Lat_xtop
	s_branch .Lat_xexit

; template <bool SEL, bool GEN>
; DI void attn_step(const KF& kv, const int kb, const int t, const int lane, const bool selbit,
;                   const LAS float* tabh, const half8 (&q)[2][2], f32x4 (&O)[2][4], const float (&nR)[2], float (&l)[2]) {
;     ...
;   for (int hp = 0; hp < 2; ++hp) {
;     float nm = nR[hp];
;     if (SEL) nm = selbit ? nm : MASKV;
;     const f32x4 c0 = {nm, nm, nm, nm};
; #pragma unroll
;     for (int kt = 0; kt < 2; ++kt) {
;       s[hp][kt] = MFMA16(kv.k[kt][0], q[hp][0], c0);
;       s[hp][kt] = MFMA16(kv.k[kt][1], q[hp][1], s[hp][kt]);
;     }
;   }
;   if (GEN) {
;     const int d0 = t - kb - fq * 4;
; #pragma unroll
;     for (int kt = 0; kt < 2; ++kt)
; #pragma unroll
;       for (int j = 0; j < 4; ++j) {
;         const int dist = d0 - (kt * 16 + j);
;         const bool bad = SEL ? (dist < 0) : ((unsigned)dist >= 512u);
;         const int ix = bad ? 130 : (dist > 128 ? 128 : dist);
; #pragma unroll
;         for (int hp = 0; hp < 2; ++hp) s[hp][kt][j] += tabh[hp * 132 + ix];
;       }
;   }
;   half8 pf[2];
; #pragma unroll
;   for (int hp = 0; hp < 2; ++hp) {
;     f32x4 p0, p1;
; #pragma unroll
;     for (int j = 0; j < 4; ++j) { p0[j] = __builtin_amdgcn_exp2f(s[hp][0][j]); p1[j] = __builtin_amdgcn_exp2f(s[hp][1][j]); }
;     l[hp] += ((p0[0] + p0[1]) + (p0[2] + p0[3])) + ((p1[0] + p1[1]) + (p1[2] + p1[3]));
;     pf[hp] = pack8(p0, p1);
;   }
; #pragma unroll
;   for (int dt = 0; dt < 4; ++dt)
; #pragma unroll
;     for (int hp = 0; hp < 2; ++hp) O[hp][dt] = MFMA16(kv.v[dt], pf[hp], O[hp][dt]);
; DI void attn_phase(const Params& p, const int layer, const int wid_s) {
;     ...
;         asm volatile("s_waitcnt vmcnt(0)" ::: "memory");
;         __syncthreads();
;         RING_ISSUE(0); RING_ISSUE(1);
; #pragma unroll 1
;         for (int si = 0; si < nsteps; ++si) {
;           asm volatile("s_waitcnt vmcnt(1) lgkmcnt(0)" ::: "memory");
;           __builtin_amdgcn_s_barrier();
;           asm volatile("" ::: "memory");
;           RING_ISSUE(si + 2);
;           const int kb = kb0 + si * 32;
;           if (kb > kmax_w || kb < lo_w) continue;
;           if (br == 1 && kb + 31 + 128 <= t0 && __ballot((selmask >> (kb >> 6)) & 1u) == 0ull) continue;
;           LAS unsigned char* slotp = ring + (si % 3) * 8192;
;           KF kv;
; #pragma unroll
;           for (int kt = 0; kt < 2; ++kt)
; #pragma unroll
.Lat_cok_y0:
	s_bitcmp1_b32 s44, 0
	s_cbranch_scc0 .Lat_yb0
	s_waitcnt lgkmcnt(4)
	v_mfma_f32_16x16x32_f16 v[60:63], v[80:83], v[120:123], v[60:63]
	v_add_f32_e32 v214, v214, v198
	v_add_f32_e32 v215, v215, v199
	v_add_f32_e32 v216, v216, v200
	v_mfma_f32_16x16x32_f16 v[56:59], v[76:79], v[120:123], v[56:59]
	v_add_f32_e32 v217, v217, v201
	v_add_f32_e32 v214, v214, v202
	v_add_f32_e32 v215, v215, v203
	v_mfma_f32_16x16x32_f16 v[52:55], v[72:75], v[120:123], v[52:55]
	v_add_f32_e32 v216, v216, v204
	v_add_f32_e32 v217, v217, v205
	v_add_f32_e32 v218, v218, v206
	v_mfma_f32_16x16x32_f16 v[48:51], v[68:71], v[120:123], v[48:51]
	v_add_f32_e32 v219, v219, v207
	v_add_f32_e32 v220, v220, v208
	v_add_f32_e32 v221, v221, v209
	v_mfma_f32_16x16x32_f16 v[44:47], v[80:83], v[124:127], v[44:47]
	v_add_f32_e32 v218, v218, v210
	v_add_f32_e32 v219, v219, v211
	v_add_f32_e32 v220, v220, v212
	v_mfma_f32_16x16x32_f16 v[40:43], v[76:79], v[124:127], v[40:43]
	v_add_f32_e32 v221, v221, v213
	s_add_i32 s8, s45, 64
	s_min_i32 s8, s8, s14
	v_mfma_f32_16x16x32_f16 v[36:39], v[72:75], v[124:127], v[36:39]
	s_mul_i32 s8, s8, s42
	s_mov_b32 s9, 0
	v_lshl_add_u64 v[238:239], v[240:241], 0, s[8:9]
	v_mfma_f32_16x16x32_f16 v[32:35], v[68:71], v[124:127], v[32:35]
	s_add_i32 m0, s22, 0x1d880
	s_nop 0
	global_load_lds_dwordx4 v[238:239], off
	s_waitcnt lgkmcnt(0)
	s_and_b32 s44, s12, 2
	s_or_b32 s44, s44, 1
	v_mfma_f32_16x16x32_f16 v[100:103], v[96:99], v[8:11], v[128:131]
	s_add_i32 s45, s45, 32
	s_add_i32 s41, s41, -1
	v_mfma_f32_16x16x32_f16 v[104:107], v[88:91], v[8:11], v[128:131]
	s_add_i32 s10, s45, 0x9f
	s_cmp_gt_i32 s10, s51
	s_cselect_b32 s11, 2, 0
	v_mfma_f32_16x16x32_f16 v[108:111], v[96:99], v[16:19], v[132:135]
	s_add_i32 s10, s45, 0x1f1
	s_cmp_le_i32 s10, s51
	s_cselect_b32 s10, 2, 0
	v_mfma_f32_16x16x32_f16 v[112:115], v[88:91], v[16:19], v[132:135]
	s_and_b32 s10, s10, s4
	s_or_b32 s11, s11, s10
	s_lshr_b32 s10, s45, 6
	v_mfma_f32_16x16x32_f16 v[100:103], v[92:95], v[12:15], v[100:103]
	v_bfe_u32 v66, v244, s10, 1
	v_cmp_ne_u32_e32 vcc, 0, v66
	v_mfma_f32_16x16x32_f16 v[104:107], v[84:87], v[12:15], v[104:107]
	s_cmp_lg_u64 vcc, 0
	s_cselect_b32 s10, 1, 0
	s_lshr_b32 s9, s11, 1
	v_mfma_f32_16x16x32_f16 v[108:111], v[92:95], v[20:23], v[108:111]
	s_or_b32 s10, s10, s9
	s_cmp_le_i32 s45, s15
	s_cselect_b32 s10, s10, 0
	v_mfma_f32_16x16x32_f16 v[112:115], v[84:87], v[20:23], v[112:115]
	s_cmp_ge_i32 s45, s40
	s_cselect_b32 s10, s10, 0
	s_or_b32 s12, s11, s10
	ds_read_b128 v[80:83], v65 offset:4096
	ds_read_b128 v[76:79], v65 offset:5120
	ds_read_b128 v[72:75], v65 offset:6144
	ds_read_b128 v[68:71], v65 offset:7168
	s_bitcmp1_b32 s44, 1
	s_cbranch_scc0 .Lat_noga_ya0
	v_add_f32_e32 v100, v100, v222
	v_add_f32_e32 v101, v101, v223
	v_add_f32_e32 v102, v102, v224
	v_add_f32_e32 v103, v103, v225
	v_add_f32_e32 v104, v104, v226
	v_add_f32_e32 v105, v105, v227
	v_add_f32_e32 v106, v106, v228
	v_add_f32_e32 v107, v107, v229
	v_add_f32_e32 v108, v108, v230
	v_add_f32_e32 v109, v109, v231
	v_add_f32_e32 v110, v110, v232
	v_add_f32_e32 v111, v111, v233
	v_add_f32_e32 v112, v112, v234
	v_add_f32_e32 v113, v113, v235
	v_add_f32_e32 v114, v114, v236
	v_add_f32_e32 v115, v115, v237

; template <bool SEL, bool GEN>
; DI void attn_step(const KF& kv, const int kb, const int t, const int lane, const bool selbit,
;                   const LAS float* tabh, const half8 (&q)[2][2], f32x4 (&O)[2][4], const float (&nR)[2], float (&l)[2]) {
;     ...
;   for (int hp = 0; hp < 2; ++hp) {
;     float nm = nR[hp];
;     if (SEL) nm = selbit ? nm : MASKV;
;     const f32x4 c0 = {nm, nm, nm, nm};
; #pragma unroll
;     for (int kt = 0; kt < 2; ++kt) {
;       s[hp][kt] = MFMA16(kv.k[kt][0], q[hp][0], c0);
;       s[hp][kt] = MFMA16(kv.k[kt][1], q[hp][1], s[hp][kt]);
;     }
;   }
;   if (GEN) {
;     const int d0 = t - kb - fq * 4;
; #pragma unroll
;     for (int kt = 0; kt < 2; ++kt)
; #pragma unroll
;       for (int j = 0; j < 4; ++j) {
;         const int dist = d0 - (kt * 16 + j);
;         const bool bad = SEL ? (dist < 0) : ((unsigned)dist >= 512u);
;         const int ix = bad ? 130 : (dist > 128 ? 128 : dist);
; #pragma unroll
;         for (int hp = 0; hp < 2; ++hp) s[hp][kt][j] += tabh[hp * 132 + ix];
;       }
; DI void attn_phase(const Params& p, const int layer, const int wid_s) {
;     ...
;         asm volatile("s_waitcnt vmcnt(0)" ::: "memory");
;         __syncthreads();
;         RING_ISSUE(0); RING_ISSUE(1);
; #pragma unroll 1
;         for (int si = 0; si < nsteps; ++si) {
;           asm volatile("s_waitcnt vmcnt(1) lgkmcnt(0)" ::: "memory");
;           __builtin_amdgcn_s_barrier();
;           asm volatile("" ::: "memory");
;           RING_ISSUE(si + 2);
;           const int kb = kb0 + si * 32;
;           if (kb > kmax_w || kb < lo_w) continue;
;           if (br == 1 && kb + 31 + 128 <= t0 && __ballot((selmask >> (kb >> 6)) & 1u) == 0ull) continue;
;           LAS unsigned char* slotp = ring + (si % 3) * 8192;
;           KF kv;
; #pragma unroll
;           for (int kt = 0; kt < 2; ++kt)
; #pragma unroll
;             for (int ks = 0; ks < 2; ++ks) kv.k[kt][ks] = *(const LAS half8*)(slotp + kread[kt][ks]);
; #pragma unroll
;           for (int dt = 0; dt < 4; ++dt) kv.v[dt] = *(const LAS half8*)(slotp + vread[dt]);
;           if (br == 1) {
;             const bool bit = (selmask >> (kb >> 6)) & 1u;
;             if (kb + 31 + 128 <= t0) attn_step<true, false>(kv, kb, t, lane, bit, tabh, q, O, nRs, l);
;             else attn_step<true, true>(kv, kb, t, lane, bit, tabh, q, O, nRs, l);
;           } else {
.Lat_yb0:
	s_waitcnt lgkmcnt(0)
	s_and_b32 s44, s12, 2
	s_or_b32 s44, s44, 1
	v_mfma_f32_16x16x32_f16 v[100:103], v[96:99], v[8:11], v[128:131]
	s_add_i32 s8, s45, 64
	s_min_i32 s8, s8, s14
	s_mul_i32 s8, s8, s42
	v_mfma_f32_16x16x32_f16 v[104:107], v[88:91], v[8:11], v[128:131]
	s_mov_b32 s9, 0
	v_lshl_add_u64 v[238:239], v[240:241], 0, s[8:9]
	s_add_i32 m0, s22, 0x1d880
	s_nop 0
	v_mfma_f32_16x16x32_f16 v[108:111], v[96:99], v[16:19], v[132:135]
	global_load_lds_dwordx4 v[238:239], off
	s_add_i32 s45, s45, 32
	s_add_i32 s41, s41, -1
	s_add_i32 s10, s45, 0x9f
	v_mfma_f32_16x16x32_f16 v[112:115], v[88:91], v[16:19], v[132:135]
	s_cmp_gt_i32 s10, s51
	s_cselect_b32 s11, 2, 0
	s_add_i32 s10, s45, 0x1f1
	s_cmp_le_i32 s10, s51
	v_mfma_f32_16x16x32_f16 v[100:103], v[92:95], v[12:15], v[100:103]
	s_cselect_b32 s10, 2, 0
	s_and_b32 s10, s10, s4
	s_or_b32 s11, s11, s10
	v_mfma_f32_16x16x32_f16 v[104:107], v[84:87], v[12:15], v[104:107]
	s_lshr_b32 s10, s45, 6
	v_bfe_u32 v66, v244, s10, 1
	v_cmp_ne_u32_e32 vcc, 0, v66
	s_cmp_lg_u64 vcc, 0
	v_mfma_f32_16x16x32_f16 v[108:111], v[92:95], v[20:23], v[108:111]
	s_cselect_b32 s10, 1, 0
	s_lshr_b32 s9, s11, 1
	s_or_b32 s10, s10, s9
	s_cmp_le_i32 s45, s15
	v_mfma_f32_16x16x32_f16 v[112:115], v[84:87], v[20:23], v[112:115]
	s_cselect_b32 s10, s10, 0
	s_cmp_ge_i32 s45, s40
	s_cselect_b32 s10, s10, 0
	s_or_b32 s12, s11, s10
	ds_read_b128 v[80:83], v65 offset:4096
	ds_read_b128 v[76:79], v65 offset:5120
	ds_read_b128 v[72:75], v65 offset:6144
	ds_read_b128 v[68:71], v65 offset:7168
	s_bitcmp1_b32 s44, 1
	s_cbranch_scc0 .Lat_noga_yb0
	v_add_f32_e32 v100, v100, v222
	v_add_f32_e32 v101, v101, v223
	v_add_f32_e32 v102, v102, v224
	v_add_f32_e32 v103, v103, v225
	v_add_f32_e32 v104, v104, v226
	v_add_f32_e32 v105, v105, v227
	v_add_f32_e32 v106, v106, v228
	v_add_f32_e32 v107, v107, v229
	v_add_f32_e32 v108, v108, v230
	v_add_f32_e32 v109, v109, v231
	v_add_f32_e32 v110, v110, v232
	v_add_f32_e32 v111, v111, v233
	v_add_f32_e32 v112, v112, v234
	v_add_f32_e32 v113, v113, v235
	v_add_f32_e32 v114, v114, v236
	v_add_f32_e32 v115, v115, v237

; #define MFMA16(a, b, c) __builtin_amdgcn_mfma_f32_16x16x32_f16((a), (b), (c), 0, 0, 0)
; #define LAS __attribute__((address_space(3)))
; template <bool SEL, bool GEN>
; DI void attn_step(const KF& kv, const int kb, const int t, const int lane, const bool selbit,
;                   const LAS float* tabh, const half8 (&q)[2][2], f32x4 (&O)[2][4], const float (&nR)[2], float (&l)[2]) {
;     ...
;     for (int j = 0; j < 4; ++j) { p0[j] = __builtin_amdgcn_exp2f(s[hp][0][j]); p1[j] = __builtin_amdgcn_exp2f(s[hp][1][j]); }
;     l[hp] += ((p0[0] + p0[1]) + (p0[2] + p0[3])) + ((p1[0] + p1[1]) + (p1[2] + p1[3]));
;     pf[hp] = pack8(p0, p1);
;   }
; #pragma unroll
;   for (int dt = 0; dt < 4; ++dt)
; #pragma unroll
;     for (int hp = 0; hp < 2; ++hp) O[hp][dt] = MFMA16(kv.v[dt], pf[hp], O[hp][dt]);
; DI void attn_phase(const Params& p, const int layer, const int wid_s) {
;     ...
;         asm volatile("s_waitcnt vmcnt(0)" ::: "memory");
;         __syncthreads();
;         RING_ISSUE(0); RING_ISSUE(1);
; #pragma unroll 1
;         for (int si = 0; si < nsteps; ++si) {
;           asm volatile("s_waitcnt vmcnt(1) lgkmcnt(0)" ::: "memory");
;           __builtin_amdgcn_s_barrier();
;           asm volatile("" ::: "memory");
;           RING_ISSUE(si + 2);
;           const int kb = kb0 + si * 32;
;           if (kb > kmax_w || kb < lo_w) continue;
;           if (br == 1 && kb + 31 + 128 <= t0 && __ballot((selmask >> (kb >> 6)) & 1u) == 0ull) continue;
;           LAS unsigned char* slotp = ring + (si % 3) * 8192;
;           KF kv;
; #pragma unroll
;           for (int kt = 0; kt < 2; ++kt)
; #pragma unroll
;             for (int ks = 0; ks < 2; ++ks) kv.k[kt][ks] = *(const LAS half8*)(slotp + kread[kt][ks]);
; #pragma unroll
;           for (int dt = 0; dt < 4; ++dt) kv.v[dt] = *(const LAS half8*)(slotp + vread[dt]);
;           if (br == 1) {
;             const bool bit = (selmask >> (kb >> 6)) & 1u;
;             if (kb + 31 + 128 <= t0) attn_step<true, false>(kv, kb, t, lane, bit, tabh, q, O, nRs, l);
;             else attn_step<true, true>(kv, kb, t, lane, bit, tabh, q, O, nRs, l);
;           } else {
;             const bool gen = (kb + 31 + 128 > t0) || (kb + 512 <= t0 + 15);
.Lat_yskip0:
	s_bitcmp1_b32 s44, 0
	s_cbranch_scc0 .Lat_yd0
	s_waitcnt lgkmcnt(0)
	v_mfma_f32_16x16x32_f16 v[60:63], v[80:83], v[120:123], v[60:63]
	v_add_f32_e32 v214, v214, v198
	v_add_f32_e32 v215, v215, v199
	v_add_f32_e32 v216, v216, v200
	v_add_f32_e32 v217, v217, v201
	v_add_f32_e32 v214, v214, v202
	v_mfma_f32_16x16x32_f16 v[56:59], v[76:79], v[120:123], v[56:59]
	v_add_f32_e32 v215, v215, v203
	v_add_f32_e32 v216, v216, v204
	v_add_f32_e32 v217, v217, v205
	v_add_f32_e32 v218, v218, v206
	v_add_f32_e32 v219, v219, v207
	v_add_f32_e32 v220, v220, v208
	v_mfma_f32_16x16x32_f16 v[52:55], v[72:75], v[120:123], v[52:55]
	v_add_f32_e32 v221, v221, v209
	v_add_f32_e32 v218, v218, v210
	v_add_f32_e32 v219, v219, v211
	v_add_f32_e32 v220, v220, v212
	v_add_f32_e32 v221, v221, v213
	s_add_i32 s8, s45, 64
	v_mfma_f32_16x16x32_f16 v[48:51], v[68:71], v[120:123], v[48:51]
	s_min_i32 s8, s8, s14
	s_mul_i32 s8, s8, s42
	s_mov_b32 s9, 0
	v_lshl_add_u64 v[238:239], v[240:241], 0, s[8:9]
	s_add_i32 m0, s22, 0x1d880
	s_nop 0
	v_mfma_f32_16x16x32_f16 v[44:47], v[80:83], v[124:127], v[44:47]
	global_load_lds_dwordx4 v[238:239], off
	s_add_i32 s45, s45, 32
	s_add_i32 s41, s41, -1
	s_add_i32 s10, s45, 0x9f
	s_cmp_gt_i32 s10, s51
	v_mfma_f32_16x16x32_f16 v[40:43], v[76:79], v[124:127], v[40:43]
	s_cselect_b32 s11, 2, 0
	s_add_i32 s10, s45, 0x1f1
	s_cmp_le_i32 s10, s51
	s_cselect_b32 s10, 2, 0
	s_and_b32 s10, s10, s4
	s_or_b32 s11, s11, s10
	v_mfma_f32_16x16x32_f16 v[36:39], v[72:75], v[124:127], v[36:39]
	s_lshr_b32 s10, s45, 6
	v_bfe_u32 v66, v244, s10, 1
	v_cmp_ne_u32_e32 vcc, 0, v66
	s_cmp_lg_u64 vcc, 0
	s_cselect_b32 s10, 1, 0
	s_lshr_b32 s9, s11, 1
	v_mfma_f32_16x16x32_f16 v[32:35], v[68:71], v[124:127], v[32:35]
	s_or_b32 s10, s10, s9
	s_cmp_le_i32 s45, s15
	s_cselect_b32 s10, s10, 0
	s_cmp_ge_i32 s45, s40
	s_cselect_b32 s10, s10, 0
	s_or_b32 s12, s11, s10
	s_mov_b32 s44, 0
	s_cmp_lg_u32 s41, 0
	s_cbranch_scc1 .Lat_ytop1
	s_branch .Lat_yexit

; template <bool SEL, bool GEN>
; DI void attn_step(const KF& kv, const int kb, const int t, const int lane, const bool selbit,
;                   const LAS float* tabh, const half8 (&q)[2][2], f32x4 (&O)[2][4], const float (&nR)[2], float (&l)[2]) {
;     ...
;   for (int hp = 0; hp < 2; ++hp) {
;     float nm = nR[hp];
;     if (SEL) nm = selbit ? nm : MASKV;
;     const f32x4 c0 = {nm, nm, nm, nm};
; #pragma unroll
;     for (int kt = 0; kt < 2; ++kt) {
;       s[hp][kt] = MFMA16(kv.k[kt][0], q[hp][0], c0);
;       s[hp][kt] = MFMA16(kv.k[kt][1], q[hp][1], s[hp][kt]);
;     }
;   }
;   if (GEN) {
;     const int d0 = t - kb - fq * 4;
; #pragma unroll
;     for (int kt = 0; kt < 2; ++kt)
; #pragma unroll
;       for (int j = 0; j < 4; ++j) {
;         const int dist = d0 - (kt * 16 + j);
;         const bool bad = SEL ? (dist < 0) : ((unsigned)dist >= 512u);
;         const int ix = bad ? 130 : (dist > 128 ? 128 : dist);
; #pragma unroll
;         for (int hp = 0; hp < 2; ++hp) s[hp][kt][j] += tabh[hp * 132 + ix];
;       }
;   }
;   half8 pf[2];
; #pragma unroll
;   for (int hp = 0; hp < 2; ++hp) {
;     f32x4 p0, p1;
; #pragma unroll
;     for (int j = 0; j < 4; ++j) { p0[j] = __builtin_amdgcn_exp2f(s[hp][0][j]); p1[j] = __builtin_amdgcn_exp2f(s[hp][1][j]); }
;     l[hp] += ((p0[0] + p0[1]) + (p0[2] + p0[3])) + ((p1[0] + p1[1]) + (p1[2] + p1[3]));
;     pf[hp] = pack8(p0, p1);
;   }
; #pragma unroll
;   for (int dt = 0; dt < 4; ++dt)
; #pragma unroll
;     for (int hp = 0; hp < 2; ++hp) O[hp][dt] = MFMA16(kv.v[dt], pf[hp], O[hp][dt]);
; DI void attn_phase(const Params& p, const int layer, const int wid_s) {
;     ...
;         asm volatile("s_waitcnt vmcnt(0)" ::: "memory");
;         __syncthreads();
;         RING_ISSUE(0); RING_ISSUE(1);
; #pragma unroll 1
;         for (int si = 0; si < nsteps; ++si) {
;           asm volatile("s_waitcnt vmcnt(1) lgkmcnt(0)" ::: "memory");
;           __builtin_amdgcn_s_barrier();
;           asm volatile("" ::: "memory");
;           RING_ISSUE(si + 2);
;           const int kb = kb0 + si * 32;
;           if (kb > kmax_w || kb < lo_w) continue;
;           if (br == 1 && kb + 31 + 128 <= t0 && __ballot((selmask >> (kb >> 6)) & 1u) == 0ull) continue;
;           LAS unsigned char* slotp = ring + (si % 3) * 8192;
;           KF kv;
; #pragma unroll
;           for (int kt = 0; kt < 2; ++kt)
; #pragma unroll
.Lat_cok_y1:
	s_bitcmp1_b32 s44, 0
	s_cbranch_scc0 .Lat_yb1
	s_waitcnt lgkmcnt(4)
	v_mfma_f32_16x16x32_f16 v[60:63], v[80:83], v[120:123], v[60:63]
	v_add_f32_e32 v214, v214, v198
	v_add_f32_e32 v215, v215, v199
	v_add_f32_e32 v216, v216, v200
	v_mfma_f32_16x16x32_f16 v[56:59], v[76:79], v[120:123], v[56:59]
	v_add_f32_e32 v217, v217, v201
	v_add_f32_e32 v214, v214, v202
	v_add_f32_e32 v215, v215, v203
	v_mfma_f32_16x16x32_f16 v[52:55], v[72:75], v[120:123], v[52:55]
	v_add_f32_e32 v216, v216, v204
	v_add_f32_e32 v217, v217, v205
	v_add_f32_e32 v218, v218, v206
	v_mfma_f32_16x16x32_f16 v[48:51], v[68:71], v[120:123], v[48:51]
	v_add_f32_e32 v219, v219, v207
	v_add_f32_e32 v220, v220, v208
	v_add_f32_e32 v221, v221, v209
	v_mfma_f32_16x16x32_f16 v[44:47], v[80:83], v[124:127], v[44:47]
	v_add_f32_e32 v218, v218, v210
	v_add_f32_e32 v219, v219, v211
	v_add_f32_e32 v220, v220, v212
	v_mfma_f32_16x16x32_f16 v[40:43], v[76:79], v[124:127], v[40:43]
	v_add_f32_e32 v221, v221, v213
	s_add_i32 s8, s45, 64
	s_min_i32 s8, s8, s14
	v_mfma_f32_16x16x32_f16 v[36:39], v[72:75], v[124:127], v[36:39]
	s_mul_i32 s8, s8, s42
	s_mov_b32 s9, 0
	v_lshl_add_u64 v[238:239], v[240:241], 0, s[8:9]
	v_mfma_f32_16x16x32_f16 v[32:35], v[68:71], v[124:127], v[32:35]
	s_add_i32 m0, s22, 0x20080
	s_nop 0
	global_load_lds_dwordx4 v[238:239], off
	s_waitcnt lgkmcnt(0)
	s_and_b32 s44, s12, 2
	s_or_b32 s44, s44, 1
	v_mfma_f32_16x16x32_f16 v[100:103], v[96:99], v[8:11], v[128:131]
	s_add_i32 s45, s45, 32
	s_add_i32 s41, s41, -1
	v_mfma_f32_16x16x32_f16 v[104:107], v[88:91], v[8:11], v[128:131]
	s_add_i32 s10, s45, 0x9f
	s_cmp_gt_i32 s10, s51
	s_cselect_b32 s11, 2, 0
	v_mfma_f32_16x16x32_f16 v[108:111], v[96:99], v[16:19], v[132:135]
	s_add_i32 s10, s45, 0x1f1
	s_cmp_le_i32 s10, s51
	s_cselect_b32 s10, 2, 0
	v_mfma_f32_16x16x32_f16 v[112:115], v[88:91], v[16:19], v[132:135]
	s_and_b32 s10, s10, s4
	s_or_b32 s11, s11, s10
	s_lshr_b32 s10, s45, 6
	v_mfma_f32_16x16x32_f16 v[100:103], v[92:95], v[12:15], v[100:103]
	v_bfe_u32 v66, v244, s10, 1
	v_cmp_ne_u32_e32 vcc, 0, v66
	v_mfma_f32_16x16x32_f16 v[104:107], v[84:87], v[12:15], v[104:107]
	s_cmp_lg_u64 vcc, 0
	s_cselect_b32 s10, 1, 0
	s_lshr_b32 s9, s11, 1
	v_mfma_f32_16x16x32_f16 v[108:111], v[92:95], v[20:23], v[108:111]
	s_or_b32 s10, s10, s9
	s_cmp_le_i32 s45, s15
	s_cselect_b32 s10, s10, 0
	v_mfma_f32_16x16x32_f16 v[112:115], v[84:87], v[20:23], v[112:115]
	s_cmp_ge_i32 s45, s40
	s_cselect_b32 s10, s10, 0
	s_or_b32 s12, s11, s10
	ds_read_b128 v[80:83], v65 offset:12288
	ds_read_b128 v[76:79], v65 offset:13312
	ds_read_b128 v[72:75], v65 offset:14336
	ds_read_b128 v[68:71], v65 offset:15360
	s_bitcmp1_b32 s44, 1
	s_cbranch_scc0 .Lat_noga_ya1
	v_add_f32_e32 v100, v100, v222
	v_add_f32_e32 v101, v101, v223
	v_add_f32_e32 v102, v102, v224
	v_add_f32_e32 v103, v103, v225
	v_add_f32_e32 v104, v104, v226
	v_add_f32_e32 v105, v105, v227
	v_add_f32_e32 v106, v106, v228
	v_add_f32_e32 v107, v107, v229
	v_add_f32_e32 v108, v108, v230
	v_add_f32_e32 v109, v109, v231
	v_add_f32_e32 v110, v110, v232
	v_add_f32_e32 v111, v111, v233
	v_add_f32_e32 v112, v112, v234
	v_add_f32_e32 v113, v113, v235
	v_add_f32_e32 v114, v114, v236
	v_add_f32_e32 v115, v115, v237

; template <bool SEL, bool GEN>
; DI void attn_step(const KF& kv, const int kb, const int t, const int lane, const bool selbit,
;                   const LAS float* tabh, const half8 (&q)[2][2], f32x4 (&O)[2][4], const float (&nR)[2], float (&l)[2]) {
;     ...
;   for (int hp = 0; hp < 2; ++hp) {
;     float nm = nR[hp];
;     if (SEL) nm = selbit ? nm : MASKV;
;     const f32x4 c0 = {nm, nm, nm, nm};
; #pragma unroll
;     for (int kt = 0; kt < 2; ++kt) {
;       s[hp][kt] = MFMA16(kv.k[kt][0], q[hp][0], c0);
;       s[hp][kt] = MFMA16(kv.k[kt][1], q[hp][1], s[hp][kt]);
;     }
;   }
;   if (GEN) {
;     const int d0 = t - kb - fq * 4;
; #pragma unroll
;     for (int kt = 0; kt < 2; ++kt)
; #pragma unroll
;       for (int j = 0; j < 4; ++j) {
;         const int dist = d0 - (kt * 16 + j);
;         const bool bad = SEL ? (dist < 0) : ((unsigned)dist >= 512u);
;         const int ix = bad ? 130 : (dist > 128 ? 128 : dist);
; #pragma unroll
;         for (int hp = 0; hp < 2; ++hp) s[hp][kt][j] += tabh[hp * 132 + ix];
;       }
; DI void attn_phase(const Params& p, const int layer, const int wid_s) {
;     ...
;         asm volatile("s_waitcnt vmcnt(0)" ::: "memory");
;         __syncthreads();
;         RING_ISSUE(0); RING_ISSUE(1);
; #pragma unroll 1
;         for (int si = 0; si < nsteps; ++si) {
;           asm volatile("s_waitcnt vmcnt(1) lgkmcnt(0)" ::: "memory");
;           __builtin_amdgcn_s_barrier();
;           asm volatile("" ::: "memory");
;           RING_ISSUE(si + 2);
;           const int kb = kb0 + si * 32;
;           if (kb > kmax_w || kb < lo_w) continue;
;           if (br == 1 && kb + 31 + 128 <= t0 && __ballot((selmask >> (kb >> 6)) & 1u) == 0ull) continue;
;           LAS unsigned char* slotp = ring + (si % 3) * 8192;
;           KF kv;
; #pragma unroll
;           for (int kt = 0; kt < 2; ++kt)
; #pragma unroll
;             for (int ks = 0; ks < 2; ++ks) kv.k[kt][ks] = *(const LAS half8*)(slotp + kread[kt][ks]);
; #pragma unroll
;           for (int dt = 0; dt < 4; ++dt) kv.v[dt] = *(const LAS half8*)(slotp + vread[dt]);
;           if (br == 1) {
;             const bool bit = (selmask >> (kb >> 6)) & 1u;
;             if (kb + 31 + 128 <= t0) attn_step<true, false>(kv, kb, t, lane, bit, tabh, q, O, nRs, l);
;             else attn_step<true, true>(kv, kb, t, lane, bit, tabh, q, O, nRs, l);
;           } else {
.Lat_yb1:
	s_waitcnt lgkmcnt(0)
	s_and_b32 s44, s12, 2
	s_or_b32 s44, s44, 1
	v_mfma_f32_16x16x32_f16 v[100:103], v[96:99], v[8:11], v[128:131]
	s_add_i32 s8, s45, 64
	s_min_i32 s8, s8, s14
	s_mul_i32 s8, s8, s42
	v_mfma_f32_16x16x32_f16 v[104:107], v[88:91], v[8:11], v[128:131]
	s_mov_b32 s9, 0
	v_lshl_add_u64 v[238:239], v[240:241], 0, s[8:9]
	s_add_i32 m0, s22, 0x20080
	s_nop 0
	v_mfma_f32_16x16x32_f16 v[108:111], v[96:99], v[16:19], v[132:135]
	global_load_lds_dwordx4 v[238:239], off
	s_add_i32 s45, s45, 32
	s_add_i32 s41, s41, -1
	s_add_i32 s10, s45, 0x9f
	v_mfma_f32_16x16x32_f16 v[112:115], v[88:91], v[16:19], v[132:135]
	s_cmp_gt_i32 s10, s51
	s_cselect_b32 s11, 2, 0
	s_add_i32 s10, s45, 0x1f1
	s_cmp_le_i32 s10, s51
	v_mfma_f32_16x16x32_f16 v[100:103], v[92:95], v[12:15], v[100:103]
	s_cselect_b32 s10, 2, 0
	s_and_b32 s10, s10, s4
	s_or_b32 s11, s11, s10
	v_mfma_f32_16x16x32_f16 v[104:107], v[84:87], v[12:15], v[104:107]
	s_lshr_b32 s10, s45, 6
	v_bfe_u32 v66, v244, s10, 1
	v_cmp_ne_u32_e32 vcc, 0, v66
	s_cmp_lg_u64 vcc, 0
	v_mfma_f32_16x16x32_f16 v[108:111], v[92:95], v[20:23], v[108:111]
	s_cselect_b32 s10, 1, 0
	s_lshr_b32 s9, s11, 1
	s_or_b32 s10, s10, s9
	s_cmp_le_i32 s45, s15
	v_mfma_f32_16x16x32_f16 v[112:115], v[84:87], v[20:23], v[112:115]
	s_cselect_b32 s10, s10, 0
	s_cmp_ge_i32 s45, s40
	s_cselect_b32 s10, s10, 0
	s_or_b32 s12, s11, s10
	ds_read_b128 v[80:83], v65 offset:12288
	ds_read_b128 v[76:79], v65 offset:13312
	ds_read_b128 v[72:75], v65 offset:14336
	ds_read_b128 v[68:71], v65 offset:15360
	s_bitcmp1_b32 s44, 1
	s_cbranch_scc0 .Lat_noga_yb1
	v_add_f32_e32 v100, v100, v222
	v_add_f32_e32 v101, v101, v223
	v_add_f32_e32 v102, v102, v224
	v_add_f32_e32 v103, v103, v225
	v_add_f32_e32 v104, v104, v226
	v_add_f32_e32 v105, v105, v227
	v_add_f32_e32 v106, v106, v228
	v_add_f32_e32 v107, v107, v229
	v_add_f32_e32 v108, v108, v230
	v_add_f32_e32 v109, v109, v231
	v_add_f32_e32 v110, v110, v232
	v_add_f32_e32 v111, v111, v233
	v_add_f32_e32 v112, v112, v234
	v_add_f32_e32 v113, v113, v235
	v_add_f32_e32 v114, v114, v236
	v_add_f32_e32 v115, v115, v237

; #define MFMA16(a, b, c) __builtin_amdgcn_mfma_f32_16x16x32_f16((a), (b), (c), 0, 0, 0)
; #define LAS __attribute__((address_space(3)))
; template <bool SEL, bool GEN>
; DI void attn_step(const KF& kv, const int kb, const int t, const int lane, const bool selbit,
;                   const LAS float* tabh, const half8 (&q)[2][2], f32x4 (&O)[2][4], const float (&nR)[2], float (&l)[2]) {
;     ...
;     for (int j = 0; j < 4; ++j) { p0[j] = __builtin_amdgcn_exp2f(s[hp][0][j]); p1[j] = __builtin_amdgcn_exp2f(s[hp][1][j]); }
;     l[hp] += ((p0[0] + p0[1]) + (p0[2] + p0[3])) + ((p1[0] + p1[1]) + (p1[2] + p1[3]));
;     pf[hp] = pack8(p0, p1);
;   }
; #pragma unroll
;   for (int dt = 0; dt < 4; ++dt)
; #pragma unroll
;     for (int hp = 0; hp < 2; ++hp) O[hp][dt] = MFMA16(kv.v[dt], pf[hp], O[hp][dt]);
; DI void attn_phase(const Params& p, const int layer, const int wid_s) {
;     ...
;         asm volatile("s_waitcnt vmcnt(0)" ::: "memory");
;         __syncthreads();
;         RING_ISSUE(0); RING_ISSUE(1);
; #pragma unroll 1
;         for (int si = 0; si < nsteps; ++si) {
;           asm volatile("s_waitcnt vmcnt(1) lgkmcnt(0)" ::: "memory");
;           __builtin_amdgcn_s_barrier();
;           asm volatile("" ::: "memory");
;           RING_ISSUE(si + 2);
;           const int kb = kb0 + si * 32;
;           if (kb > kmax_w || kb < lo_w) continue;
;           if (br == 1 && kb + 31 + 128 <= t0 && __ballot((selmask >> (kb >> 6)) & 1u) == 0ull) continue;
;           LAS unsigned char* slotp = ring + (si % 3) * 8192;
;           KF kv;
; #pragma unroll
;           for (int kt = 0; kt < 2; ++kt)
; #pragma unroll
;             for (int ks = 0; ks < 2; ++ks) kv.k[kt][ks] = *(const LAS half8*)(slotp + kread[kt][ks]);
; #pragma unroll
;           for (int dt = 0; dt < 4; ++dt) kv.v[dt] = *(const LAS half8*)(slotp + vread[dt]);
;           if (br == 1) {
;             const bool bit = (selmask >> (kb >> 6)) & 1u;
;             if (kb + 31 + 128 <= t0) attn_step<true, false>(kv, kb, t, lane, bit, tabh, q, O, nRs, l);
;             else attn_step<true, true>(kv, kb, t, lane, bit, tabh, q, O, nRs, l);
;           } else {
;             const bool gen = (kb + 31 + 128 > t0) || (kb + 512 <= t0 + 15);
.Lat_yskip1:
	s_bitcmp1_b32 s44, 0
	s_cbranch_scc0 .Lat_yd1
	s_waitcnt lgkmcnt(0)
	v_mfma_f32_16x16x32_f16 v[60:63], v[80:83], v[120:123], v[60:63]
	v_add_f32_e32 v214, v214, v198
	v_add_f32_e32 v215, v215, v199
	v_add_f32_e32 v216, v216, v200
	v_add_f32_e32 v217, v217, v201
	v_add_f32_e32 v214, v214, v202
	v_mfma_f32_16x16x32_f16 v[56:59], v[76:79], v[120:123], v[56:59]
	v_add_f32_e32 v215, v215, v203
	v_add_f32_e32 v216, v216, v204
	v_add_f32_e32 v217, v217, v205
	v_add_f32_e32 v218, v218, v206
	v_add_f32_e32 v219, v219, v207
	v_add_f32_e32 v220, v220, v208
	v_mfma_f32_16x16x32_f16 v[52:55], v[72:75], v[120:123], v[52:55]
	v_add_f32_e32 v221, v221, v209
	v_add_f32_e32 v218, v218, v210
	v_add_f32_e32 v219, v219, v211
	v_add_f32_e32 v220, v220, v212
	v_add_f32_e32 v221, v221, v213
	s_add_i32 s8, s45, 64
	v_mfma_f32_16x16x32_f16 v[48:51], v[68:71], v[120:123], v[48:51]
	s_min_i32 s8, s8, s14
	s_mul_i32 s8, s8, s42
	s_mov_b32 s9, 0
	v_lshl_add_u64 v[238:239], v[240:241], 0, s[8:9]
	s_add_i32 m0, s22, 0x20080
	s_nop 0
	v_mfma_f32_16x16x32_f16 v[44:47], v[80:83], v[124:127], v[44:47]
	global_load_lds_dwordx4 v[238:239], off
	s_add_i32 s45, s45, 32
	s_add_i32 s41, s41, -1
	s_add_i32 s10, s45, 0x9f
	s_cmp_gt_i32 s10, s51
	v_mfma_f32_16x16x32_f16 v[40:43], v[76:79], v[124:127], v[40:43]
	s_cselect_b32 s11, 2, 0
	s_add_i32 s10, s45, 0x1f1
	s_cmp_le_i32 s10, s51
	s_cselect_b32 s10, 2, 0
	s_and_b32 s10, s10, s4
	s_or_b32 s11, s11, s10
	v_mfma_f32_16x16x32_f16 v[36:39], v[72:75], v[124:127], v[36:39]
	s_lshr_b32 s10, s45, 6
	v_bfe_u32 v66, v244, s10, 1
	v_cmp_ne_u32_e32 vcc, 0, v66
	s_cmp_lg_u64 vcc, 0
	s_cselect_b32 s10, 1, 0
	s_lshr_b32 s9, s11, 1
	v_mfma_f32_16x16x32_f16 v[32:35], v[68:71], v[124:127], v[32:35]
	s_or_b32 s10, s10, s9
	s_cmp_le_i32 s45, s15
	s_cselect_b32 s10, s10, 0
	s_cmp_ge_i32 s45, s40
	s_cselect_b32 s10, s10, 0
	s_or_b32 s12, s11, s10
	s_mov_b32 s44, 0
	s_cmp_lg_u32 s41, 0
	s_cbranch_scc1 .Lat_ytop2
	s_branch .Lat_yexit

; template <bool SEL, bool GEN>
; DI void attn_step(const KF& kv, const int kb, const int t, const int lane, const bool selbit,
;                   const LAS float* tabh, const half8 (&q)[2][2], f32x4 (&O)[2][4], const float (&nR)[2], float (&l)[2]) {
;     ...
;   for (int hp = 0; hp < 2; ++hp) {
;     float nm = nR[hp];
;     if (SEL) nm = selbit ? nm : MASKV;
;     const f32x4 c0 = {nm, nm, nm, nm};
; #pragma unroll
;     for (int kt = 0; kt < 2; ++kt) {
;       s[hp][kt] = MFMA16(kv.k[kt][0], q[hp][0], c0);
;       s[hp][kt] = MFMA16(kv.k[kt][1], q[hp][1], s[hp][kt]);
;     }
;   }
;   if (GEN) {
;     const int d0 = t - kb - fq * 4;
; #pragma unroll
;     for (int kt = 0; kt < 2; ++kt)
; #pragma unroll
;       for (int j = 0; j < 4; ++j) {
;         const int dist = d0 - (kt * 16 + j);
;         const bool bad = SEL ? (dist < 0) : ((unsigned)dist >= 512u);
;         const int ix = bad ? 130 : (dist > 128 ? 128 : dist);
; #pragma unroll
;         for (int hp = 0; hp < 2; ++hp) s[hp][kt][j] += tabh[hp * 132 + ix];
;       }
;   }
;   half8 pf[2];
; #pragma unroll
;   for (int hp = 0; hp < 2; ++hp) {
;     f32x4 p0, p1;
; #pragma unroll
;     for (int j = 0; j < 4; ++j) { p0[j] = __builtin_amdgcn_exp2f(s[hp][0][j]); p1[j] = __builtin_amdgcn_exp2f(s[hp][1][j]); }
;     l[hp] += ((p0[0] + p0[1]) + (p0[2] + p0[3])) + ((p1[0] + p1[1]) + (p1[2] + p1[3]));
;     pf[hp] = pack8(p0, p1);
;   }
; #pragma unroll
;   for (int dt = 0; dt < 4; ++dt)
; #pragma unroll
;     for (int hp = 0; hp < 2; ++hp) O[hp][dt] = MFMA16(kv.v[dt], pf[hp], O[hp][dt]);
; DI void attn_phase(const Params& p, const int layer, const int wid_s) {
;     ...
;         asm volatile("s_waitcnt vmcnt(0)" ::: "memory");
;         __syncthreads();
;         RING_ISSUE(0); RING_ISSUE(1);
; #pragma unroll 1
;         for (int si = 0; si < nsteps; ++si) {
;           asm volatile("s_waitcnt vmcnt(1) lgkmcnt(0)" ::: "memory");
;           __builtin_amdgcn_s_barrier();
;           asm volatile("" ::: "memory");
;           RING_ISSUE(si + 2);
;           const int kb = kb0 + si * 32;
;           if (kb > kmax_w || kb < lo_w) continue;
;           if (br == 1 && kb + 31 + 128 <= t0 && __ballot((selmask >> (kb >> 6)) & 1u) == 0ull) continue;
;           LAS unsigned char* slotp = ring + (si % 3) * 8192;
;           KF kv;
; #pragma unroll
;           for (int kt = 0; kt < 2; ++kt)
; #pragma unroll
.Lat_cok_y2:
	s_bitcmp1_b32 s44, 0
	s_cbranch_scc0 .Lat_yb2
	s_waitcnt lgkmcnt(4)
	v_mfma_f32_16x16x32_f16 v[60:63], v[80:83], v[120:123], v[60:63]
	v_add_f32_e32 v214, v214, v198
	v_add_f32_e32 v215, v215, v199
	v_add_f32_e32 v216, v216, v200
	v_mfma_f32_16x16x32_f16 v[56:59], v[76:79], v[120:123], v[56:59]
	v_add_f32_e32 v217, v217, v201
	v_add_f32_e32 v214, v214, v202
	v_add_f32_e32 v215, v215, v203
	v_mfma_f32_16x16x32_f16 v[52:55], v[72:75], v[120:123], v[52:55]
	v_add_f32_e32 v216, v216, v204
	v_add_f32_e32 v217, v217, v205
	v_add_f32_e32 v218, v218, v206
	v_mfma_f32_16x16x32_f16 v[48:51], v[68:71], v[120:123], v[48:51]
	v_add_f32_e32 v219, v219, v207
	v_add_f32_e32 v220, v220, v208
	v_add_f32_e32 v221, v221, v209
	v_mfma_f32_16x16x32_f16 v[44:47], v[80:83], v[124:127], v[44:47]
	v_add_f32_e32 v218, v218, v210
	v_add_f32_e32 v219, v219, v211
	v_add_f32_e32 v220, v220, v212
	v_mfma_f32_16x16x32_f16 v[40:43], v[76:79], v[124:127], v[40:43]
	v_add_f32_e32 v221, v221, v213
	s_add_i32 s8, s45, 64
	s_min_i32 s8, s8, s14
	v_mfma_f32_16x16x32_f16 v[36:39], v[72:75], v[124:127], v[36:39]
	s_mul_i32 s8, s8, s42
	s_mov_b32 s9, 0
	v_lshl_add_u64 v[238:239], v[240:241], 0, s[8:9]
	v_mfma_f32_16x16x32_f16 v[32:35], v[68:71], v[124:127], v[32:35]
	s_add_i32 m0, s22, 0x19880
	s_nop 0
	global_load_lds_dwordx4 v[238:239], off
	s_waitcnt lgkmcnt(0)
	s_and_b32 s44, s12, 2
	s_or_b32 s44, s44, 1
	v_mfma_f32_16x16x32_f16 v[100:103], v[96:99], v[8:11], v[128:131]
	s_add_i32 s45, s45, 32
	s_add_i32 s41, s41, -1
	v_mfma_f32_16x16x32_f16 v[104:107], v[88:91], v[8:11], v[128:131]
	s_add_i32 s10, s45, 0x9f
	s_cmp_gt_i32 s10, s51
	s_cselect_b32 s11, 2, 0
	v_mfma_f32_16x16x32_f16 v[108:111], v[96:99], v[16:19], v[132:135]
	s_add_i32 s10, s45, 0x1f1
	s_cmp_le_i32 s10, s51
	s_cselect_b32 s10, 2, 0
	v_mfma_f32_16x16x32_f16 v[112:115], v[88:91], v[16:19], v[132:135]
	s_and_b32 s10, s10, s4
	s_or_b32 s11, s11, s10
	s_lshr_b32 s10, s45, 6
	v_mfma_f32_16x16x32_f16 v[100:103], v[92:95], v[12:15], v[100:103]
	v_bfe_u32 v66, v244, s10, 1
	v_cmp_ne_u32_e32 vcc, 0, v66
	v_mfma_f32_16x16x32_f16 v[104:107], v[84:87], v[12:15], v[104:107]
	s_cmp_lg_u64 vcc, 0
	s_cselect_b32 s10, 1, 0
	s_lshr_b32 s9, s11, 1
	v_mfma_f32_16x16x32_f16 v[108:111], v[92:95], v[20:23], v[108:111]
	s_or_b32 s10, s10, s9
	s_cmp_le_i32 s45, s15
	s_cselect_b32 s10, s10, 0
	v_mfma_f32_16x16x32_f16 v[112:115], v[84:87], v[20:23], v[112:115]
	s_cmp_ge_i32 s45, s40
	s_cselect_b32 s10, s10, 0
	s_or_b32 s12, s11, s10
	ds_read_b128 v[80:83], v65 offset:20480
	ds_read_b128 v[76:79], v65 offset:21504
	ds_read_b128 v[72:75], v65 offset:22528
	ds_read_b128 v[68:71], v65 offset:23552
	s_bitcmp1_b32 s44, 1
	s_cbranch_scc0 .Lat_noga_ya2
	v_add_f32_e32 v100, v100, v222
	v_add_f32_e32 v101, v101, v223
	v_add_f32_e32 v102, v102, v224
	v_add_f32_e32 v103, v103, v225
	v_add_f32_e32 v104, v104, v226
	v_add_f32_e32 v105, v105, v227
	v_add_f32_e32 v106, v106, v228
	v_add_f32_e32 v107, v107, v229
	v_add_f32_e32 v108, v108, v230
	v_add_f32_e32 v109, v109, v231
	v_add_f32_e32 v110, v110, v232
	v_add_f32_e32 v111, v111, v233
	v_add_f32_e32 v112, v112, v234
	v_add_f32_e32 v113, v113, v235
	v_add_f32_e32 v114, v114, v236
	v_add_f32_e32 v115, v115, v237

; template <bool SEL, bool GEN>
; DI void attn_step(const KF& kv, const int kb, const int t, const int lane, const bool selbit,
;                   const LAS float* tabh, const half8 (&q)[2][2], f32x4 (&O)[2][4], const float (&nR)[2], float (&l)[2]) {
;     ...
;   for (int hp = 0; hp < 2; ++hp) {
;     float nm = nR[hp];
;     if (SEL) nm = selbit ? nm : MASKV;
;     const f32x4 c0 = {nm, nm, nm, nm};
; #pragma unroll
;     for (int kt = 0; kt < 2; ++kt) {
;       s[hp][kt] = MFMA16(kv.k[kt][0], q[hp][0], c0);
;       s[hp][kt] = MFMA16(kv.k[kt][1], q[hp][1], s[hp][kt]);
;     }
;   }
;   if (GEN) {
;     const int d0 = t - kb - fq * 4;
; #pragma unroll
;     for (int kt = 0; kt < 2; ++kt)
; #pragma unroll
;       for (int j = 0; j < 4; ++j) {
;         const int dist = d0 - (kt * 16 + j);
;         const bool bad = SEL ? (dist < 0) : ((unsigned)dist >= 512u);
;         const int ix = bad ? 130 : (dist > 128 ? 128 : dist);
; #pragma unroll
;         for (int hp = 0; hp < 2; ++hp) s[hp][kt][j] += tabh[hp * 132 + ix];
;       }
; DI void attn_phase(const Params& p, const int layer, const int wid_s) {
;     ...
;         asm volatile("s_waitcnt vmcnt(0)" ::: "memory");
;         __syncthreads();
;         RING_ISSUE(0); RING_ISSUE(1);
; #pragma unroll 1
;         for (int si = 0; si < nsteps; ++si) {
;           asm volatile("s_waitcnt vmcnt(1) lgkmcnt(0)" ::: "memory");
;           __builtin_amdgcn_s_barrier();
;           asm volatile("" ::: "memory");
;           RING_ISSUE(si + 2);
;           const int kb = kb0 + si * 32;
;           if (kb > kmax_w || kb < lo_w) continue;
;           if (br == 1 && kb + 31 + 128 <= t0 && __ballot((selmask >> (kb >> 6)) & 1u) == 0ull) continue;
;           LAS unsigned char* slotp = ring + (si % 3) * 8192;
;           KF kv;
; #pragma unroll
;           for (int kt = 0; kt < 2; ++kt)
; #pragma unroll
;             for (int ks = 0; ks < 2; ++ks) kv.k[kt][ks] = *(const LAS half8*)(slotp + kread[kt][ks]);
; #pragma unroll
;           for (int dt = 0; dt < 4; ++dt) kv.v[dt] = *(const LAS half8*)(slotp + vread[dt]);
;           if (br == 1) {
;             const bool bit = (selmask >> (kb >> 6)) & 1u;
;             if (kb + 31 + 128 <= t0) attn_step<true, false>(kv, kb, t, lane, bit, tabh, q, O, nRs, l);
;             else attn_step<true, true>(kv, kb, t, lane, bit, tabh, q, O, nRs, l);
;           } else {
.Lat_yb2:
	s_waitcnt lgkmcnt(0)
	s_and_b32 s44, s12, 2
	s_or_b32 s44, s44, 1
	v_mfma_f32_16x16x32_f16 v[100:103], v[96:99], v[8:11], v[128:131]
	s_add_i32 s8, s45, 64
	s_min_i32 s8, s8, s14
	s_mul_i32 s8, s8, s42
	v_mfma_f32_16x16x32_f16 v[104:107], v[88:91], v[8:11], v[128:131]
	s_mov_b32 s9, 0
	v_lshl_add_u64 v[238:239], v[240:241], 0, s[8:9]
	s_add_i32 m0, s22, 0x19880
	s_nop 0
	v_mfma_f32_16x16x32_f16 v[108:111], v[96:99], v[16:19], v[132:135]
	global_load_lds_dwordx4 v[238:239], off
	s_add_i32 s45, s45, 32
	s_add_i32 s41, s41, -1
	s_add_i32 s10, s45, 0x9f
	v_mfma_f32_16x16x32_f16 v[112:115], v[88:91], v[16:19], v[132:135]
	s_cmp_gt_i32 s10, s51
	s_cselect_b32 s11, 2, 0
	s_add_i32 s10, s45, 0x1f1
	s_cmp_le_i32 s10, s51
	v_mfma_f32_16x16x32_f16 v[100:103], v[92:95], v[12:15], v[100:103]
	s_cselect_b32 s10, 2, 0
	s_and_b32 s10, s10, s4
	s_or_b32 s11, s11, s10
	v_mfma_f32_16x16x32_f16 v[104:107], v[84:87], v[12:15], v[104:107]
	s_lshr_b32 s10, s45, 6
	v_bfe_u32 v66, v244, s10, 1
	v_cmp_ne_u32_e32 vcc, 0, v66
	s_cmp_lg_u64 vcc, 0
	v_mfma_f32_16x16x32_f16 v[108:111], v[92:95], v[20:23], v[108:111]
	s_cselect_b32 s10, 1, 0
	s_lshr_b32 s9, s11, 1
	s_or_b32 s10, s10, s9
	s_cmp_le_i32 s45, s15
	v_mfma_f32_16x16x32_f16 v[112:115], v[84:87], v[20:23], v[112:115]
	s_cselect_b32 s10, s10, 0
	s_cmp_ge_i32 s45, s40
	s_cselect_b32 s10, s10, 0
	s_or_b32 s12, s11, s10
	ds_read_b128 v[80:83], v65 offset:20480
	ds_read_b128 v[76:79], v65 offset:21504
	ds_read_b128 v[72:75], v65 offset:22528
	ds_read_b128 v[68:71], v65 offset:23552
	s_bitcmp1_b32 s44, 1
	s_cbranch_scc0 .Lat_noga_yb2
	v_add_f32_e32 v100, v100, v222
	v_add_f32_e32 v101, v101, v223
	v_add_f32_e32 v102, v102, v224
	v_add_f32_e32 v103, v103, v225
	v_add_f32_e32 v104, v104, v226
	v_add_f32_e32 v105, v105, v227
	v_add_f32_e32 v106, v106, v228
	v_add_f32_e32 v107, v107, v229
	v_add_f32_e32 v108, v108, v230
	v_add_f32_e32 v109, v109, v231
	v_add_f32_e32 v110, v110, v232
	v_add_f32_e32 v111, v111, v233
	v_add_f32_e32 v112, v112, v234
	v_add_f32_e32 v113, v113, v235
	v_add_f32_e32 v114, v114, v236
	v_add_f32_e32 v115, v115, v237

; #define MFMA16(a, b, c) __builtin_amdgcn_mfma_f32_16x16x32_f16((a), (b), (c), 0, 0, 0)
; #define LAS __attribute__((address_space(3)))
; template <bool SEL, bool GEN>
; DI void attn_step(const KF& kv, const int kb, const int t, const int lane, const bool selbit,
;                   const LAS float* tabh, const half8 (&q)[2][2], f32x4 (&O)[2][4], const float (&nR)[2], float (&l)[2]) {
;     ...
;     for (int j = 0; j < 4; ++j) { p0[j] = __builtin_amdgcn_exp2f(s[hp][0][j]); p1[j] = __builtin_amdgcn_exp2f(s[hp][1][j]); }
;     l[hp] += ((p0[0] + p0[1]) + (p0[2] + p0[3])) + ((p1[0] + p1[1]) + (p1[2] + p1[3]));
;     pf[hp] = pack8(p0, p1);
;   }
; #pragma unroll
;   for (int dt = 0; dt < 4; ++dt)
; #pragma unroll
;     for (int hp = 0; hp < 2; ++hp) O[hp][dt] = MFMA16(kv.v[dt], pf[hp], O[hp][dt]);
; DI void attn_phase(const Params& p, const int layer, const int wid_s) {
;     ...
;         asm volatile("s_waitcnt vmcnt(0)" ::: "memory");
;         __syncthreads();
;         RING_ISSUE(0); RING_ISSUE(1);
; #pragma unroll 1
;         for (int si = 0; si < nsteps; ++si) {
;           asm volatile("s_waitcnt vmcnt(1) lgkmcnt(0)" ::: "memory");
;           __builtin_amdgcn_s_barrier();
;           asm volatile("" ::: "memory");
;           RING_ISSUE(si + 2);
;           const int kb = kb0 + si * 32;
;           if (kb > kmax_w || kb < lo_w) continue;
;           if (br == 1 && kb + 31 + 128 <= t0 && __ballot((selmask >> (kb >> 6)) & 1u) == 0ull) continue;
;           LAS unsigned char* slotp = ring + (si % 3) * 8192;
;           KF kv;
; #pragma unroll
;           for (int kt = 0; kt < 2; ++kt)
; #pragma unroll
;             for (int ks = 0; ks < 2; ++ks) kv.k[kt][ks] = *(const LAS half8*)(slotp + kread[kt][ks]);
; #pragma unroll
;           for (int dt = 0; dt < 4; ++dt) kv.v[dt] = *(const LAS half8*)(slotp + vread[dt]);
;           if (br == 1) {
;             const bool bit = (selmask >> (kb >> 6)) & 1u;
;             if (kb + 31 + 128 <= t0) attn_step<true, false>(kv, kb, t, lane, bit, tabh, q, O, nRs, l);
;             else attn_step<true, true>(kv, kb, t, lane, bit, tabh, q, O, nRs, l);
;           } else {
;             const bool gen = (kb + 31 + 128 > t0) || (kb + 512 <= t0 + 15);
.Lat_yskip2:
	s_bitcmp1_b32 s44, 0
	s_cbranch_scc0 .Lat_yd2
	s_waitcnt lgkmcnt(0)
	v_mfma_f32_16x16x32_f16 v[60:63], v[80:83], v[120:123], v[60:63]
	v_add_f32_e32 v214, v214, v198
	v_add_f32_e32 v215, v215, v199
	v_add_f32_e32 v216, v216, v200
	v_add_f32_e32 v217, v217, v201
	v_add_f32_e32 v214, v214, v202
	v_mfma_f32_16x16x32_f16 v[56:59], v[76:79], v[120:123], v[56:59]
	v_add_f32_e32 v215, v215, v203
	v_add_f32_e32 v216, v216, v204
	v_add_f32_e32 v217, v217, v205
	v_add_f32_e32 v218, v218, v206
	v_add_f32_e32 v219, v219, v207
	v_add_f32_e32 v220, v220, v208
	v_mfma_f32_16x16x32_f16 v[52:55], v[72:75], v[120:123], v[52:55]
	v_add_f32_e32 v221, v221, v209
	v_add_f32_e32 v218, v218, v210
	v_add_f32_e32 v219, v219, v211
	v_add_f32_e32 v220, v220, v212
	v_add_f32_e32 v221, v221, v213
	s_add_i32 s8, s45, 64
	v_mfma_f32_16x16x32_f16 v[48:51], v[68:71], v[120:123], v[48:51]
	s_min_i32 s8, s8, s14
	s_mul_i32 s8, s8, s42
	s_mov_b32 s9, 0
	v_lshl_add_u64 v[238:239], v[240:241], 0, s[8:9]
	s_add_i32 m0, s22, 0x19880
	s_nop 0
	v_mfma_f32_16x16x32_f16 v[44:47], v[80:83], v[124:127], v[44:47]
	global_load_lds_dwordx4 v[238:239], off
	s_add_i32 s45, s45, 32
	s_add_i32 s41, s41, -1
	s_add_i32 s10, s45, 0x9f
	s_cmp_gt_i32 s10, s51
	v_mfma_f32_16x16x32_f16 v[40:43], v[76:79], v[124:127], v[40:43]
	s_cselect_b32 s11, 2, 0
	s_add_i32 s10, s45, 0x1f1
	s_cmp_le_i32 s10, s51
	s_cselect_b32 s10, 2, 0
	s_and_b32 s10, s10, s4
	s_or_b32 s11, s11, s10
	v_mfma_f32_16x16x32_f16 v[36:39], v[72:75], v[124:127], v[36:39]
	s_lshr_b32 s10, s45, 6
	v_bfe_u32 v66, v244, s10, 1
	v_cmp_ne_u32_e32 vcc, 0, v66
	s_cmp_lg_u64 vcc, 0
	s_cselect_b32 s10, 1, 0
	s_lshr_b32 s9, s11, 1
	v_mfma_f32_16x16x32_f16 v[32:35], v[68:71], v[124:127], v[32:35]
	s_or_b32 s10, s10, s9
	s_cmp_le_i32 s45, s15
	s_cselect_b32 s10, s10, 0
	s_cmp_ge_i32 s45, s40
	s_cselect_b32 s10, s10, 0
	s_or_b32 s12, s11, s10
	s_mov_b32 s44, 0
	s_cmp_lg_u32 s41, 0
	s_cbranch_scc1 .Lat_ytop3
	s_branch .Lat_yexit

; template <bool SEL, bool GEN>
; DI void attn_step(const KF& kv, const int kb, const int t, const int lane, const bool selbit,
;                   const LAS float* tabh, const half8 (&q)[2][2], f32x4 (&O)[2][4], const float (&nR)[2], float (&l)[2]) {
;     ...
;   for (int hp = 0; hp < 2; ++hp) {
;     float nm = nR[hp];
;     if (SEL) nm = selbit ? nm : MASKV;
;     const f32x4 c0 = {nm, nm, nm, nm};
; #pragma unroll
;     for (int kt = 0; kt < 2; ++kt) {
;       s[hp][kt] = MFMA16(kv.k[kt][0], q[hp][0], c0);
;       s[hp][kt] = MFMA16(kv.k[kt][1], q[hp][1], s[hp][kt]);
;     }
;   }
;   if (GEN) {
;     const int d0 = t - kb - fq * 4;
; #pragma unroll
;     for (int kt = 0; kt < 2; ++kt)
; #pragma unroll
;       for (int j = 0; j < 4; ++j) {
;         const int dist = d0 - (kt * 16 + j);
;         const bool bad = SEL ? (dist < 0) : ((unsigned)dist >= 512u);
;         const int ix = bad ? 130 : (dist > 128 ? 128 : dist);
; #pragma unroll
;         for (int hp = 0; hp < 2; ++hp) s[hp][kt][j] += tabh[hp * 132 + ix];
;       }
;   }
;   half8 pf[2];
; #pragma unroll
;   for (int hp = 0; hp < 2; ++hp) {
;     f32x4 p0, p1;
; #pragma unroll
;     for (int j = 0; j < 4; ++j) { p0[j] = __builtin_amdgcn_exp2f(s[hp][0][j]); p1[j] = __builtin_amdgcn_exp2f(s[hp][1][j]); }
;     l[hp] += ((p0[0] + p0[1]) + (p0[2] + p0[3])) + ((p1[0] + p1[1]) + (p1[2] + p1[3]));
;     pf[hp] = pack8(p0, p1);
;   }
; #pragma unroll
;   for (int dt = 0; dt < 4; ++dt)
; #pragma unroll
;     for (int hp = 0; hp < 2; ++hp) O[hp][dt] = MFMA16(kv.v[dt], pf[hp], O[hp][dt]);
; DI void attn_phase(const Params& p, const int layer, const int wid_s) {
;     ...
;         asm volatile("s_waitcnt vmcnt(0)" ::: "memory");
;         __syncthreads();
;         RING_ISSUE(0); RING_ISSUE(1);
; #pragma unroll 1
;         for (int si = 0; si < nsteps; ++si) {
;           asm volatile("s_waitcnt vmcnt(1) lgkmcnt(0)" ::: "memory");
;           __builtin_amdgcn_s_barrier();
;           asm volatile("" ::: "memory");
;           RING_ISSUE(si + 2);
;           const int kb = kb0 + si * 32;
;           if (kb > kmax_w || kb < lo_w) continue;
;           if (br == 1 && kb + 31 + 128 <= t0 && __ballot((selmask >> (kb >> 6)) & 1u) == 0ull) continue;
;           LAS unsigned char* slotp = ring + (si % 3) * 8192;
;           KF kv;
; #pragma unroll
;           for (int kt = 0; kt < 2; ++kt)
; #pragma unroll
.Lat_cok_y3:
	s_bitcmp1_b32 s44, 0
	s_cbranch_scc0 .Lat_yb3
	s_waitcnt lgkmcnt(4)
	v_mfma_f32_16x16x32_f16 v[60:63], v[80:83], v[120:123], v[60:63]
	v_add_f32_e32 v214, v214, v198
	v_add_f32_e32 v215, v215, v199
	v_add_f32_e32 v216, v216, v200
	v_mfma_f32_16x16x32_f16 v[56:59], v[76:79], v[120:123], v[56:59]
	v_add_f32_e32 v217, v217, v201
	v_add_f32_e32 v214, v214, v202
	v_add_f32_e32 v215, v215, v203
	v_mfma_f32_16x16x32_f16 v[52:55], v[72:75], v[120:123], v[52:55]
	v_add_f32_e32 v216, v216, v204
	v_add_f32_e32 v217, v217, v205
	v_add_f32_e32 v218, v218, v206
	v_mfma_f32_16x16x32_f16 v[48:51], v[68:71], v[120:123], v[48:51]
	v_add_f32_e32 v219, v219, v207
	v_add_f32_e32 v220, v220, v208
	v_add_f32_e32 v221, v221, v209
	v_mfma_f32_16x16x32_f16 v[44:47], v[80:83], v[124:127], v[44:47]
	v_add_f32_e32 v218, v218, v210
	v_add_f32_e32 v219, v219, v211
	v_add_f32_e32 v220, v220, v212
	v_mfma_f32_16x16x32_f16 v[40:43], v[76:79], v[124:127], v[40:43]
	v_add_f32_e32 v221, v221, v213
	s_add_i32 s8, s45, 64
	s_min_i32 s8, s8, s14
	v_mfma_f32_16x16x32_f16 v[36:39], v[72:75], v[124:127], v[36:39]
	s_mul_i32 s8, s8, s42
	s_mov_b32 s9, 0
	v_lshl_add_u64 v[238:239], v[240:241], 0, s[8:9]
	v_mfma_f32_16x16x32_f16 v[32:35], v[68:71], v[124:127], v[32:35]
	s_add_i32 m0, s22, 0x1b880
	s_nop 0
	global_load_lds_dwordx4 v[238:239], off
	s_waitcnt lgkmcnt(0)
	s_and_b32 s44, s12, 2
	s_or_b32 s44, s44, 1
	v_mfma_f32_16x16x32_f16 v[100:103], v[96:99], v[8:11], v[128:131]
	s_add_i32 s45, s45, 32
	s_add_i32 s41, s41, -1
	v_mfma_f32_16x16x32_f16 v[104:107], v[88:91], v[8:11], v[128:131]
	s_add_i32 s10, s45, 0x9f
	s_cmp_gt_i32 s10, s51
	s_cselect_b32 s11, 2, 0
	v_mfma_f32_16x16x32_f16 v[108:111], v[96:99], v[16:19], v[132:135]
	s_add_i32 s10, s45, 0x1f1
	s_cmp_le_i32 s10, s51
	s_cselect_b32 s10, 2, 0
	v_mfma_f32_16x16x32_f16 v[112:115], v[88:91], v[16:19], v[132:135]
	s_and_b32 s10, s10, s4
	s_or_b32 s11, s11, s10
	s_lshr_b32 s10, s45, 6
	v_mfma_f32_16x16x32_f16 v[100:103], v[92:95], v[12:15], v[100:103]
	v_bfe_u32 v66, v244, s10, 1
	v_cmp_ne_u32_e32 vcc, 0, v66
	v_mfma_f32_16x16x32_f16 v[104:107], v[84:87], v[12:15], v[104:107]
	s_cmp_lg_u64 vcc, 0
	s_cselect_b32 s10, 1, 0
	s_lshr_b32 s9, s11, 1
	v_mfma_f32_16x16x32_f16 v[108:111], v[92:95], v[20:23], v[108:111]
	s_or_b32 s10, s10, s9
	s_cmp_le_i32 s45, s15
	s_cselect_b32 s10, s10, 0
	v_mfma_f32_16x16x32_f16 v[112:115], v[84:87], v[20:23], v[112:115]
	s_cmp_ge_i32 s45, s40
	s_cselect_b32 s10, s10, 0
	s_or_b32 s12, s11, s10
	ds_read_b128 v[80:83], v65 offset:30720
	ds_read_b128 v[76:79], v65 offset:31744
	ds_read_b128 v[72:75], v65 offset:32768
	ds_read_b128 v[68:71], v65 offset:33792
	s_bitcmp1_b32 s44, 1
	s_cbranch_scc0 .Lat_noga_ya3
	v_add_f32_e32 v100, v100, v222
	v_add_f32_e32 v101, v101, v223
	v_add_f32_e32 v102, v102, v224
	v_add_f32_e32 v103, v103, v225
	v_add_f32_e32 v104, v104, v226
	v_add_f32_e32 v105, v105, v227
	v_add_f32_e32 v106, v106, v228
	v_add_f32_e32 v107, v107, v229
	v_add_f32_e32 v108, v108, v230
	v_add_f32_e32 v109, v109, v231
	v_add_f32_e32 v110, v110, v232
	v_add_f32_e32 v111, v111, v233
	v_add_f32_e32 v112, v112, v234
	v_add_f32_e32 v113, v113, v235
	v_add_f32_e32 v114, v114, v236
	v_add_f32_e32 v115, v115, v237

; template <bool SEL, bool GEN>
; DI void attn_step(const KF& kv, const int kb, const int t, const int lane, const bool selbit,
;                   const LAS float* tabh, const half8 (&q)[2][2], f32x4 (&O)[2][4], const float (&nR)[2], float (&l)[2]) {
;     ...
;   for (int hp = 0; hp < 2; ++hp) {
;     float nm = nR[hp];
;     if (SEL) nm = selbit ? nm : MASKV;
;     const f32x4 c0 = {nm, nm, nm, nm};
; #pragma unroll
;     for (int kt = 0; kt < 2; ++kt) {
;       s[hp][kt] = MFMA16(kv.k[kt][0], q[hp][0], c0);
;       s[hp][kt] = MFMA16(kv.k[kt][1], q[hp][1], s[hp][kt]);
;     }
;   }
;   if (GEN) {
;     const int d0 = t - kb - fq * 4;
; #pragma unroll
;     for (int kt = 0; kt < 2; ++kt)
; #pragma unroll
;       for (int j = 0; j < 4; ++j) {
;         const int dist = d0 - (kt * 16 + j);
;         const bool bad = SEL ? (dist < 0) : ((unsigned)dist >= 512u);
;         const int ix = bad ? 130 : (dist > 128 ? 128 : dist);
; #pragma unroll
;         for (int hp = 0; hp < 2; ++hp) s[hp][kt][j] += tabh[hp * 132 + ix];
;       }
; DI void attn_phase(const Params& p, const int layer, const int wid_s) {
;     ...
;         asm volatile("s_waitcnt vmcnt(0)" ::: "memory");
;         __syncthreads();
;         RING_ISSUE(0); RING_ISSUE(1);
; #pragma unroll 1
;         for (int si = 0; si < nsteps; ++si) {
;           asm volatile("s_waitcnt vmcnt(1) lgkmcnt(0)" ::: "memory");
;           __builtin_amdgcn_s_barrier();
;           asm volatile("" ::: "memory");
;           RING_ISSUE(si + 2);
;           const int kb = kb0 + si * 32;
;           if (kb > kmax_w || kb < lo_w) continue;
;           if (br == 1 && kb + 31 + 128 <= t0 && __ballot((selmask >> (kb >> 6)) & 1u) == 0ull) continue;
;           LAS unsigned char* slotp = ring + (si % 3) * 8192;
;           KF kv;
; #pragma unroll
;           for (int kt = 0; kt < 2; ++kt)
; #pragma unroll
;             for (int ks = 0; ks < 2; ++ks) kv.k[kt][ks] = *(const LAS half8*)(slotp + kread[kt][ks]);
; #pragma unroll
;           for (int dt = 0; dt < 4; ++dt) kv.v[dt] = *(const LAS half8*)(slotp + vread[dt]);
;           if (br == 1) {
;             const bool bit = (selmask >> (kb >> 6)) & 1u;
;             if (kb + 31 + 128 <= t0) attn_step<true, false>(kv, kb, t, lane, bit, tabh, q, O, nRs, l);
;             else attn_step<true, true>(kv, kb, t, lane, bit, tabh, q, O, nRs, l);
;           } else {
.Lat_yb3:
	s_waitcnt lgkmcnt(0)
	s_and_b32 s44, s12, 2
	s_or_b32 s44, s44, 1
	v_mfma_f32_16x16x32_f16 v[100:103], v[96:99], v[8:11], v[128:131]
	s_add_i32 s8, s45, 64
	s_min_i32 s8, s8, s14
	s_mul_i32 s8, s8, s42
	v_mfma_f32_16x16x32_f16 v[104:107], v[88:91], v[8:11], v[128:131]
	s_mov_b32 s9, 0
	v_lshl_add_u64 v[238:239], v[240:241], 0, s[8:9]
	s_add_i32 m0, s22, 0x1b880
	s_nop 0
	v_mfma_f32_16x16x32_f16 v[108:111], v[96:99], v[16:19], v[132:135]
	global_load_lds_dwordx4 v[238:239], off
	s_add_i32 s45, s45, 32
	s_add_i32 s41, s41, -1
	s_add_i32 s10, s45, 0x9f
	v_mfma_f32_16x16x32_f16 v[112:115], v[88:91], v[16:19], v[132:135]
	s_cmp_gt_i32 s10, s51
	s_cselect_b32 s11, 2, 0
	s_add_i32 s10, s45, 0x1f1
	s_cmp_le_i32 s10, s51
	v_mfma_f32_16x16x32_f16 v[100:103], v[92:95], v[12:15], v[100:103]
	s_cselect_b32 s10, 2, 0
	s_and_b32 s10, s10, s4
	s_or_b32 s11, s11, s10
	v_mfma_f32_16x16x32_f16 v[104:107], v[84:87], v[12:15], v[104:107]
	s_lshr_b32 s10, s45, 6
	v_bfe_u32 v66, v244, s10, 1
	v_cmp_ne_u32_e32 vcc, 0, v66
	s_cmp_lg_u64 vcc, 0
	v_mfma_f32_16x16x32_f16 v[108:111], v[92:95], v[20:23], v[108:111]
	s_cselect_b32 s10, 1, 0
	s_lshr_b32 s9, s11, 1
	s_or_b32 s10, s10, s9
	s_cmp_le_i32 s45, s15
	v_mfma_f32_16x16x32_f16 v[112:115], v[84:87], v[20:23], v[112:115]
	s_cselect_b32 s10, s10, 0
	s_cmp_ge_i32 s45, s40
	s_cselect_b32 s10, s10, 0
	s_or_b32 s12, s11, s10
	ds_read_b128 v[80:83], v65 offset:30720
	ds_read_b128 v[76:79], v65 offset:31744
	ds_read_b128 v[72:75], v65 offset:32768
	ds_read_b128 v[68:71], v65 offset:33792
	s_bitcmp1_b32 s44, 1
	s_cbranch_scc0 .Lat_noga_yb3
	v_add_f32_e32 v100, v100, v222
	v_add_f32_e32 v101, v101, v223
	v_add_f32_e32 v102, v102, v224
	v_add_f32_e32 v103, v103, v225
	v_add_f32_e32 v104, v104, v226
	v_add_f32_e32 v105, v105, v227
	v_add_f32_e32 v106, v106, v228
	v_add_f32_e32 v107, v107, v229
	v_add_f32_e32 v108, v108, v230
	v_add_f32_e32 v109, v109, v231
	v_add_f32_e32 v110, v110, v232
	v_add_f32_e32 v111, v111, v233
	v_add_f32_e32 v112, v112, v234
	v_add_f32_e32 v113, v113, v235
	v_add_f32_e32 v114, v114, v236
	v_add_f32_e32 v115, v115, v237

; #define MFMA16(a, b, c) __builtin_amdgcn_mfma_f32_16x16x32_f16((a), (b), (c), 0, 0, 0)
; #define LAS __attribute__((address_space(3)))
; template <bool SEL, bool GEN>
; DI void attn_step(const KF& kv, const int kb, const int t, const int lane, const bool selbit,
;                   const LAS float* tabh, const half8 (&q)[2][2], f32x4 (&O)[2][4], const float (&nR)[2], float (&l)[2]) {
;     ...
;     for (int j = 0; j < 4; ++j) { p0[j] = __builtin_amdgcn_exp2f(s[hp][0][j]); p1[j] = __builtin_amdgcn_exp2f(s[hp][1][j]); }
;     l[hp] += ((p0[0] + p0[1]) + (p0[2] + p0[3])) + ((p1[0] + p1[1]) + (p1[2] + p1[3]));
;     pf[hp] = pack8(p0, p1);
;   }
; #pragma unroll
;   for (int dt = 0; dt < 4; ++dt)
; #pragma unroll
;     for (int hp = 0; hp < 2; ++hp) O[hp][dt] = MFMA16(kv.v[dt], pf[hp], O[hp][dt]);
; DI void attn_phase(const Params& p, const int layer, const int wid_s) {
;     ...
;         asm volatile("s_waitcnt vmcnt(0)" ::: "memory");
;         __syncthreads();
;         RING_ISSUE(0); RING_ISSUE(1);
; #pragma unroll 1
;         for (int si = 0; si < nsteps; ++si) {
;           asm volatile("s_waitcnt vmcnt(1) lgkmcnt(0)" ::: "memory");
;           __builtin_amdgcn_s_barrier();
;           asm volatile("" ::: "memory");
;           RING_ISSUE(si + 2);
;           const int kb = kb0 + si * 32;
;           if (kb > kmax_w || kb < lo_w) continue;
;           if (br == 1 && kb + 31 + 128 <= t0 && __ballot((selmask >> (kb >> 6)) & 1u) == 0ull) continue;
;           LAS unsigned char* slotp = ring + (si % 3) * 8192;
;           KF kv;
; #pragma unroll
;           for (int kt = 0; kt < 2; ++kt)
; #pragma unroll
;             for (int ks = 0; ks < 2; ++ks) kv.k[kt][ks] = *(const LAS half8*)(slotp + kread[kt][ks]);
; #pragma unroll
;           for (int dt = 0; dt < 4; ++dt) kv.v[dt] = *(const LAS half8*)(slotp + vread[dt]);
;           if (br == 1) {
;             const bool bit = (selmask >> (kb >> 6)) & 1u;
;             if (kb + 31 + 128 <= t0) attn_step<true, false>(kv, kb, t, lane, bit, tabh, q, O, nRs, l);
;             else attn_step<true, true>(kv, kb, t, lane, bit, tabh, q, O, nRs, l);
;           } else {
;             const bool gen = (kb + 31 + 128 > t0) || (kb + 512 <= t0 + 15);
.Lat_yskip3:
	s_bitcmp1_b32 s44, 0
	s_cbranch_scc0 .Lat_yd3
	s_waitcnt lgkmcnt(0)
	v_mfma_f32_16x16x32_f16 v[60:63], v[80:83], v[120:123], v[60:63]
	v_add_f32_e32 v214, v214, v198
	v_add_f32_e32 v215, v215, v199
	v_add_f32_e32 v216, v216, v200
	v_add_f32_e32 v217, v217, v201
	v_add_f32_e32 v214, v214, v202
	v_mfma_f32_16x16x32_f16 v[56:59], v[76:79], v[120:123], v[56:59]
	v_add_f32_e32 v215, v215, v203
	v_add_f32_e32 v216, v216, v204
	v_add_f32_e32 v217, v217, v205
	v_add_f32_e32 v218, v218, v206
	v_add_f32_e32 v219, v219, v207
	v_add_f32_e32 v220, v220, v208
	v_mfma_f32_16x16x32_f16 v[52:55], v[72:75], v[120:123], v[52:55]
	v_add_f32_e32 v221, v221, v209
	v_add_f32_e32 v218, v218, v210
	v_add_f32_e32 v219, v219, v211
	v_add_f32_e32 v220, v220, v212
	v_add_f32_e32 v221, v221, v213
	s_add_i32 s8, s45, 64
	v_mfma_f32_16x16x32_f16 v[48:51], v[68:71], v[120:123], v[48:51]
	s_min_i32 s8, s8, s14
	s_mul_i32 s8, s8, s42
	s_mov_b32 s9, 0
	v_lshl_add_u64 v[238:239], v[240:241], 0, s[8:9]
	s_add_i32 m0, s22, 0x1b880
	s_nop 0
	v_mfma_f32_16x16x32_f16 v[44:47], v[80:83], v[124:127], v[44:47]
	global_load_lds_dwordx4 v[238:239], off
	s_add_i32 s45, s45, 32
	s_add_i32 s41, s41, -1
	s_add_i32 s10, s45, 0x9f
	s_cmp_gt_i32 s10, s51
	v_mfma_f32_16x16x32_f16 v[40:43], v[76:79], v[124:127], v[40:43]
	s_cselect_b32 s11, 2, 0
	s_add_i32 s10, s45, 0x1f1
	s_cmp_le_i32 s10, s51
	s_cselect_b32 s10, 2, 0
	s_and_b32 s10, s10, s4
	s_or_b32 s11, s11, s10
	v_mfma_f32_16x16x32_f16 v[36:39], v[72:75], v[124:127], v[36:39]
	s_lshr_b32 s10, s45, 6
	v_bfe_u32 v66, v244, s10, 1
	v_cmp_ne_u32_e32 vcc, 0, v66
	s_cmp_lg_u64 vcc, 0
	s_cselect_b32 s10, 1, 0
	s_lshr_b32 s9, s11, 1
	v_mfma_f32_16x16x32_f16 v[32:35], v[68:71], v[124:127], v[32:35]
	s_or_b32 s10, s10, s9
	s_cmp_le_i32 s45, s15
	s_cselect_b32 s10, s10, 0
	s_cmp_ge_i32 s45, s40
	s_cselect_b32 s10, s10, 0
	s_or_b32 s12, s11, s10
	s_mov_b32 s44, 0
	s_cmp_lg_u32 s41, 0
	s_cbranch_scc1 .Lat_ytop
	s_branch .Lat_yexit
